# speedup vs baseline: 1.0286x; 1.0169x over previous
; __device__ __forceinline__ float sum32(float v) { auto rr = __builtin_amdgcn_permlane32_swap(__float_as_uint(v), __float_as_uint(v), false, false); return __uint_as_float(rr[0]) + __uint_as_float(rr[1]); }
; template <int MODE>
; __device__ __forceinline__ void attn_unit(const UnitP& P, ALAS char* lds, const float* __restrict__ sub_gain, const int wv0, unsigned& hgen, unsigned* qctr, const int xcd) {
;     ...
;         if (active && map == 0) {
;             const float inv = 1.f / lsum;
;             float ss = 0.f;
; #pragma unroll
;             for (int d0 = 0; d0 < 4; ++d0)
; #pragma unroll
;                 for (int r = 0; r < 16; ++r) { const float v = o[d0][r] * inv - ex[(d0 * 16 + r) * 64]; o[d0][r] = v; ss += v * v; }
;             ss = sum32(ss);
.LBB0_330:
	s_cmp_eq_u32 s12, 0
	s_cselect_b64 s[6:7], -1, 0
	s_and_b64 s[4:5], s[4:5], s[6:7]
	s_andn2_b64 vcc, exec, s[4:5]
	s_cbranch_vccnz .LBB0_334
	v_div_scale_f32 v65, s[4:5], v64, v64, 1.0
	v_rcp_f32_e32 v66, v65
	v_div_scale_f32 v67, vcc, 1.0, v64, 1.0
	v_readlane_b32 s2, v252, 44
	v_fma_f32 v68, -v65, v66, 1.0
	v_fmac_f32_e32 v66, v68, v66
	v_mul_f32_e32 v68, v67, v66
	v_fma_f32 v69, -v65, v68, v67
	v_fmac_f32_e32 v68, v69, v66
	v_fma_f32 v65, -v65, v68, v67
	v_div_fmas_f32 v65, v65, v66, v68
	ds_read2st64_b32 v[66:67], v79 offset1:1
	v_div_fixup_f32 v78, v65, v64, 1.0
	ds_read2st64_b32 v[64:65], v79 offset0:2 offset1:3
	ds_read2st64_b32 v[68:69], v79 offset0:4 offset1:5
	ds_read2st64_b32 v[70:71], v79 offset0:6 offset1:7
	v_cmp_gt_u32_e32 vcc, s2, v174
	s_waitcnt lgkmcnt(0)
	v_pk_fma_f32 v[74:75], v[48:49], v[78:79], v[66:67] op_sel_hi:[1,0,1] neg_lo:[0,0,1] neg_hi:[0,0,1]
	s_nop 0
	v_mul_f32_e32 v48, v75, v75
	v_pk_fma_f32 v[48:49], v[74:75], v[74:75], v[48:49] op_sel_hi:[1,1,0]
	v_pk_fma_f32 v[76:77], v[50:51], v[78:79], v[64:65] op_sel_hi:[1,0,1] neg_lo:[0,0,1] neg_hi:[0,0,1]
	v_pk_fma_f32 v[72:73], v[52:53], v[78:79], v[68:69] op_sel_hi:[1,0,1] neg_lo:[0,0,1] neg_hi:[0,0,1]
	v_pk_fma_f32 v[48:49], v[76:77], v[76:77], v[48:49]
	v_mul_f32_e32 v50, v77, v77
	v_pk_add_f32 v[48:49], v[48:49], v[50:51] op_sel_hi:[1,0]
	ds_read2st64_b32 v[52:53], v79 offset0:8 offset1:9
	v_pk_fma_f32 v[48:49], v[72:73], v[72:73], v[48:49]
	v_mul_f32_e32 v50, v73, v73
	v_pk_add_f32 v[48:49], v[48:49], v[50:51] op_sel_hi:[1,0]
	v_pk_fma_f32 v[70:71], v[54:55], v[78:79], v[70:71] op_sel_hi:[1,0,1] neg_lo:[0,0,1] neg_hi:[0,0,1]
	s_waitcnt lgkmcnt(0)
	v_pk_fma_f32 v[66:67], v[56:57], v[78:79], v[52:53] op_sel_hi:[1,0,1] neg_lo:[0,0,1] neg_hi:[0,0,1]
	v_pk_fma_f32 v[48:49], v[70:71], v[70:71], v[48:49]
	v_mul_f32_e32 v50, v71, v71
	v_pk_add_f32 v[48:49], v[48:49], v[50:51] op_sel_hi:[1,0]
	ds_read2st64_b32 v[50:51], v79 offset0:10 offset1:11
	ds_read2st64_b32 v[54:55], v79 offset0:12 offset1:13
	ds_read2st64_b32 v[80:81], v79 offset0:14 offset1:15
	v_pk_fma_f32 v[48:49], v[66:67], v[66:67], v[48:49]
	v_mul_f32_e32 v52, v67, v67
	v_pk_add_f32 v[48:49], v[48:49], v[52:53] op_sel_hi:[1,0]
	s_waitcnt lgkmcnt(0)
	v_pk_fma_f32 v[68:69], v[58:59], v[78:79], v[50:51] op_sel_hi:[1,0,1] neg_lo:[0,0,1] neg_hi:[0,0,1]
	v_pk_fma_f32 v[64:65], v[60:61], v[78:79], v[54:55] op_sel_hi:[1,0,1] neg_lo:[0,0,1] neg_hi:[0,0,1]
	v_pk_fma_f32 v[48:49], v[68:69], v[68:69], v[48:49]
	v_mul_f32_e32 v50, v69, v69
	v_pk_add_f32 v[48:49], v[48:49], v[50:51] op_sel_hi:[1,0]
	ds_read2st64_b32 v[52:53], v79 offset0:16 offset1:17
	v_pk_fma_f32 v[48:49], v[64:65], v[64:65], v[48:49]
	v_mul_f32_e32 v50, v65, v65
	v_pk_add_f32 v[48:49], v[48:49], v[50:51] op_sel_hi:[1,0]
	v_pk_fma_f32 v[62:63], v[62:63], v[78:79], v[80:81] op_sel_hi:[1,0,1] neg_lo:[0,0,1] neg_hi:[0,0,1]
	s_waitcnt lgkmcnt(0)
	v_pk_fma_f32 v[58:59], v[32:33], v[78:79], v[52:53] op_sel_hi:[1,0,1] neg_lo:[0,0,1] neg_hi:[0,0,1]
	v_pk_fma_f32 v[48:49], v[62:63], v[62:63], v[48:49]
	v_mul_f32_e32 v50, v63, v63
	v_pk_add_f32 v[48:49], v[48:49], v[50:51] op_sel_hi:[1,0]
	ds_read2st64_b32 v[50:51], v79 offset0:18 offset1:19
	ds_read2st64_b32 v[54:55], v79 offset0:20 offset1:21
	ds_read2st64_b32 v[80:81], v79 offset0:22 offset1:23
	v_pk_fma_f32 v[32:33], v[58:59], v[58:59], v[48:49]
	v_mul_f32_e32 v48, v59, v59
	v_pk_add_f32 v[32:33], v[32:33], v[48:49] op_sel_hi:[1,0]
	s_waitcnt lgkmcnt(0)
	v_pk_fma_f32 v[60:61], v[34:35], v[78:79], v[50:51] op_sel_hi:[1,0,1] neg_lo:[0,0,1] neg_hi:[0,0,1]
	v_pk_fma_f32 v[56:57], v[36:37], v[78:79], v[54:55] op_sel_hi:[1,0,1] neg_lo:[0,0,1] neg_hi:[0,0,1]
	v_pk_fma_f32 v[32:33], v[60:61], v[60:61], v[32:33]
	v_mul_f32_e32 v34, v61, v61
	v_pk_add_f32 v[32:33], v[32:33], v[34:35] op_sel_hi:[1,0]
	ds_read2st64_b32 v[36:37], v79 offset0:24 offset1:25
	v_pk_fma_f32 v[32:33], v[56:57], v[56:57], v[32:33]
	v_mul_f32_e32 v34, v57, v57
	v_pk_add_f32 v[32:33], v[32:33], v[34:35] op_sel_hi:[1,0]
	v_pk_fma_f32 v[54:55], v[38:39], v[78:79], v[80:81] op_sel_hi:[1,0,1] neg_lo:[0,0,1] neg_hi:[0,0,1]
	s_waitcnt lgkmcnt(0)
	v_pk_fma_f32 v[50:51], v[40:41], v[78:79], v[36:37] op_sel_hi:[1,0,1] neg_lo:[0,0,1] neg_hi:[0,0,1]
	v_pk_fma_f32 v[32:33], v[54:55], v[54:55], v[32:33]
	v_mul_f32_e32 v34, v55, v55
	v_pk_add_f32 v[32:33], v[32:33], v[34:35] op_sel_hi:[1,0]
	ds_read2st64_b32 v[34:35], v79 offset0:26 offset1:27
	ds_read2st64_b32 v[38:39], v79 offset0:28 offset1:29
	ds_read2st64_b32 v[80:81], v79 offset0:30 offset1:31
	v_pk_fma_f32 v[32:33], v[50:51], v[50:51], v[32:33]
	v_mul_f32_e32 v36, v51, v51
	v_pk_add_f32 v[32:33], v[32:33], v[36:37] op_sel_hi:[1,0]
	s_waitcnt lgkmcnt(0)
	v_pk_fma_f32 v[52:53], v[42:43], v[78:79], v[34:35] op_sel_hi:[1,0,1] neg_lo:[0,0,1] neg_hi:[0,0,1]
	v_pk_fma_f32 v[48:49], v[44:45], v[78:79], v[38:39] op_sel_hi:[1,0,1] neg_lo:[0,0,1] neg_hi:[0,0,1]
	v_pk_fma_f32 v[32:33], v[52:53], v[52:53], v[32:33]
	v_mul_f32_e32 v34, v53, v53
	v_pk_add_f32 v[32:33], v[32:33], v[34:35] op_sel_hi:[1,0]
	ds_read2st64_b32 v[36:37], v79 offset0:32 offset1:33
	v_pk_fma_f32 v[32:33], v[48:49], v[48:49], v[32:33]
	v_mul_f32_e32 v34, v49, v49
	v_pk_add_f32 v[32:33], v[32:33], v[34:35] op_sel_hi:[1,0]
	v_pk_fma_f32 v[44:45], v[46:47], v[78:79], v[80:81] op_sel_hi:[1,0,1] neg_lo:[0,0,1] neg_hi:[0,0,1]
	s_waitcnt lgkmcnt(0)
	v_pk_fma_f32 v[40:41], v[16:17], v[78:79], v[36:37] op_sel_hi:[1,0,1] neg_lo:[0,0,1] neg_hi:[0,0,1]
	v_pk_fma_f32 v[32:33], v[44:45], v[44:45], v[32:33]
	v_mul_f32_e32 v34, v45, v45
	v_pk_add_f32 v[32:33], v[32:33], v[34:35] op_sel_hi:[1,0]
	ds_read2st64_b32 v[34:35], v79 offset0:34 offset1:35
	ds_read2st64_b32 v[38:39], v79 offset0:36 offset1:37
	ds_read2st64_b32 v[46:47], v79 offset0:38 offset1:39
	v_pk_fma_f32 v[16:17], v[40:41], v[40:41], v[32:33]
	v_mul_f32_e32 v32, v41, v41
	v_pk_add_f32 v[16:17], v[16:17], v[32:33] op_sel_hi:[1,0]
	s_waitcnt lgkmcnt(0)
; __device__ __forceinline__ float sum32(float v) { auto rr = __builtin_amdgcn_permlane32_swap(__float_as_uint(v), __float_as_uint(v), false, false); return __uint_as_float(rr[0]) + __uint_as_float(rr[1]); }
; template <int MODE>
; __device__ __forceinline__ void attn_unit(const UnitP& P, ALAS char* lds, const float* __restrict__ sub_gain, const int wv0, unsigned& hgen, unsigned* qctr, const int xcd) {
;     ...
; #pragma unroll
;             for (int d0 = 0; d0 < 4; ++d0)
; #pragma unroll
;                 for (int r = 0; r < 16; ++r) { const float v = o[d0][r] * inv - ex[(d0 * 16 + r) * 64]; o[d0][r] = v; ss += v * v; }
;             ss = sum32(ss);
;             const float rn = rsqrtf(ss * (1.f / 128.f) + 1e-6f) * 0.8f;
;             if (qrow < P.nq && P.dry == 0) {
	v_pk_fma_f32 v[42:43], v[18:19], v[78:79], v[34:35] op_sel_hi:[1,0,1] neg_lo:[0,0,1] neg_hi:[0,0,1]
	v_pk_fma_f32 v[38:39], v[20:21], v[78:79], v[38:39] op_sel_hi:[1,0,1] neg_lo:[0,0,1] neg_hi:[0,0,1]
	v_pk_fma_f32 v[16:17], v[42:43], v[42:43], v[16:17]
	v_mul_f32_e32 v18, v43, v43
	v_pk_add_f32 v[16:17], v[16:17], v[18:19] op_sel_hi:[1,0]
	ds_read2st64_b32 v[20:21], v79 offset0:40 offset1:41
	v_pk_fma_f32 v[16:17], v[38:39], v[38:39], v[16:17]
	v_mul_f32_e32 v18, v39, v39
	v_pk_add_f32 v[16:17], v[16:17], v[18:19] op_sel_hi:[1,0]
	v_pk_fma_f32 v[36:37], v[22:23], v[78:79], v[46:47] op_sel_hi:[1,0,1] neg_lo:[0,0,1] neg_hi:[0,0,1]
	s_waitcnt lgkmcnt(0)
	v_pk_fma_f32 v[32:33], v[24:25], v[78:79], v[20:21] op_sel_hi:[1,0,1] neg_lo:[0,0,1] neg_hi:[0,0,1]
	v_pk_fma_f32 v[16:17], v[36:37], v[36:37], v[16:17]
	v_mul_f32_e32 v18, v37, v37
	v_pk_add_f32 v[16:17], v[16:17], v[18:19] op_sel_hi:[1,0]
	ds_read2st64_b32 v[18:19], v79 offset0:42 offset1:43
	ds_read2st64_b32 v[22:23], v79 offset0:44 offset1:45
	ds_read2st64_b32 v[46:47], v79 offset0:46 offset1:47
	v_pk_fma_f32 v[16:17], v[32:33], v[32:33], v[16:17]
	v_mul_f32_e32 v20, v33, v33
	v_pk_add_f32 v[16:17], v[16:17], v[20:21] op_sel_hi:[1,0]
	s_waitcnt lgkmcnt(0)
	v_pk_fma_f32 v[34:35], v[26:27], v[78:79], v[18:19] op_sel_hi:[1,0,1] neg_lo:[0,0,1] neg_hi:[0,0,1]
	v_pk_fma_f32 v[26:27], v[28:29], v[78:79], v[22:23] op_sel_hi:[1,0,1] neg_lo:[0,0,1] neg_hi:[0,0,1]
	v_pk_fma_f32 v[16:17], v[34:35], v[34:35], v[16:17]
	v_mul_f32_e32 v18, v35, v35
	v_pk_add_f32 v[16:17], v[16:17], v[18:19] op_sel_hi:[1,0]
	ds_read2st64_b32 v[20:21], v79 offset0:48 offset1:49
	v_pk_fma_f32 v[16:17], v[26:27], v[26:27], v[16:17]
	v_mul_f32_e32 v18, v27, v27
	v_pk_add_f32 v[16:17], v[16:17], v[18:19] op_sel_hi:[1,0]
	v_pk_fma_f32 v[24:25], v[30:31], v[78:79], v[46:47] op_sel_hi:[1,0,1] neg_lo:[0,0,1] neg_hi:[0,0,1]
	s_waitcnt lgkmcnt(0)
	v_pk_fma_f32 v[20:21], v[0:1], v[78:79], v[20:21] op_sel_hi:[1,0,1] neg_lo:[0,0,1] neg_hi:[0,0,1]
	v_pk_fma_f32 v[16:17], v[24:25], v[24:25], v[16:17]
	v_mul_f32_e32 v18, v25, v25
	v_pk_add_f32 v[16:17], v[16:17], v[18:19] op_sel_hi:[1,0]
	ds_read2st64_b32 v[18:19], v79 offset0:50 offset1:51
	ds_read2st64_b32 v[28:29], v79 offset0:52 offset1:53
	ds_read2st64_b32 v[30:31], v79 offset0:54 offset1:55
	v_pk_fma_f32 v[0:1], v[20:21], v[20:21], v[16:17]
	v_mul_f32_e32 v16, v21, v21
	v_pk_add_f32 v[0:1], v[0:1], v[16:17] op_sel_hi:[1,0]
	s_waitcnt lgkmcnt(0)
	v_pk_fma_f32 v[22:23], v[2:3], v[78:79], v[18:19] op_sel_hi:[1,0,1] neg_lo:[0,0,1] neg_hi:[0,0,1]
	v_pk_fma_f32 v[18:19], v[4:5], v[78:79], v[28:29] op_sel_hi:[1,0,1] neg_lo:[0,0,1] neg_hi:[0,0,1]
	v_pk_fma_f32 v[0:1], v[22:23], v[22:23], v[0:1]
	v_mul_f32_e32 v2, v23, v23
	v_pk_add_f32 v[0:1], v[0:1], v[2:3] op_sel_hi:[1,0]
	ds_read2st64_b32 v[4:5], v79 offset0:56 offset1:57
	v_pk_fma_f32 v[0:1], v[18:19], v[18:19], v[0:1]
	v_mul_f32_e32 v2, v19, v19
	v_pk_add_f32 v[0:1], v[0:1], v[2:3] op_sel_hi:[1,0]
	v_pk_fma_f32 v[16:17], v[6:7], v[78:79], v[30:31] op_sel_hi:[1,0,1] neg_lo:[0,0,1] neg_hi:[0,0,1]
	s_waitcnt lgkmcnt(0)
	v_pk_fma_f32 v[8:9], v[8:9], v[78:79], v[4:5] op_sel_hi:[1,0,1] neg_lo:[0,0,1] neg_hi:[0,0,1]
	v_pk_fma_f32 v[0:1], v[16:17], v[16:17], v[0:1]
	v_mul_f32_e32 v2, v17, v17
	v_pk_add_f32 v[0:1], v[0:1], v[2:3] op_sel_hi:[1,0]
	ds_read2st64_b32 v[2:3], v79 offset0:58 offset1:59
	ds_read2st64_b32 v[6:7], v79 offset0:60 offset1:61
	ds_read2st64_b32 v[28:29], v79 offset0:62 offset1:63
	v_pk_fma_f32 v[0:1], v[8:9], v[8:9], v[0:1]
	v_mul_f32_e32 v4, v9, v9
	v_pk_add_f32 v[0:1], v[0:1], v[4:5] op_sel_hi:[1,0]
	s_waitcnt lgkmcnt(0)
	v_pk_fma_f32 v[10:11], v[10:11], v[78:79], v[2:3] op_sel_hi:[1,0,1] neg_lo:[0,0,1] neg_hi:[0,0,1]
	s_nop 0
	v_pk_fma_f32 v[0:1], v[10:11], v[10:11], v[0:1]
	v_mul_f32_e32 v2, v11, v11
	v_pk_add_f32 v[0:1], v[0:1], v[2:3] op_sel_hi:[1,0]
	v_pk_fma_f32 v[2:3], v[12:13], v[78:79], v[6:7] op_sel_hi:[1,0,1] neg_lo:[0,0,1] neg_hi:[0,0,1]
	s_nop 0
	v_pk_fma_f32 v[0:1], v[2:3], v[2:3], v[0:1]
	v_mul_f32_e32 v4, v3, v3
	v_pk_add_f32 v[4:5], v[0:1], v[4:5] op_sel_hi:[1,0]
	v_pk_fma_f32 v[0:1], v[14:15], v[78:79], v[28:29] op_sel_hi:[1,0,1] neg_lo:[0,0,1] neg_hi:[0,0,1]
	s_nop 0
	v_pk_fma_f32 v[4:5], v[0:1], v[0:1], v[4:5]
	v_mul_f32_e32 v6, v1, v1
	v_pk_add_f32 v[4:5], v[4:5], v[6:7] op_sel_hi:[1,0]
	s_nop 0
	v_mov_b32_e32 v5, v4
	s_nop 1
	v_permlane32_swap_b32_e32 v4, v5
	s_and_saveexec_b64 s[10:11], vcc
	s_cbranch_execz .LBB0_333
; __device__ __forceinline__ float sum32(float v) { auto rr = __builtin_amdgcn_permlane32_swap(__float_as_uint(v), __float_as_uint(v), false, false); return __uint_as_float(rr[0]) + __uint_as_float(rr[1]); }
; __device__ __forceinline__ unsigned cvtpk(float lo, float hi) { f32x2 v = {lo, hi}; bf16x2_t b = __builtin_convertvector(v, bf16x2_t); return __builtin_bit_cast(unsigned, b); }
; __device__ __forceinline__ float bf2f(unsigned u16) { return __uint_as_float(u16 << 16); }
; __device__ __forceinline__ float silu(float g) { return g / (1.f + __expf(-g)); }
; template <int MODE>
; __device__ __forceinline__ void attn_unit(const UnitP& P, ALAS char* lds, const float* __restrict__ sub_gain, const int wv0, unsigned& hgen, unsigned* qctr, const int xcd) {
;     ...
;             ss = sum32(ss);
;             const float rn = rsqrtf(ss * (1.f / 128.f) + 1e-6f) * 0.8f;
;             if (qrow < P.nq && P.dry == 0) {
;                 const bf16_t* gp = P.G + (size_t)qrow * 8192 + 4 * hi;
;                 bf16_t* mp = P.Mo + (size_t)qrow * 2048 + 4 * hi;
; #pragma unroll
;                 for (int d0 = 0; d0 < 4; ++d0)
; #pragma unroll
;                     for (int g = 0; g < 4; ++g) {
;                         const u32x2 gg = *(const u32x2*)(gp + 32 * d0 + 8 * g);
;                         const f32x4 sg = *(const f32x4*)(sub_gain + 32 * d0 + 8 * g + 4 * hi);
;                         const float y0 = o[d0][4 * g + 0] * rn * sg[0] * silu(bf2f(gg.x & 0xffffu)), y1 = o[d0][4 * g + 1] * rn * sg[1] * silu(bf2f(gg.x >> 16));
;                         const float y2 = o[d0][4 * g + 2] * rn * sg[2] * silu(bf2f(gg.y & 0xffffu)), y3 = o[d0][4 * g + 3] * rn * sg[3] * silu(bf2f(gg.y >> 16));
;                         u32x2 w; w.x = cvtpk(y0, y1); w.y = cvtpk(y2, y3);
;                         *(u32x2*)(mp + 32 * d0 + 8 * g) = w;
	v_readlane_b32 s4, v252, 40
	v_mov_b32_e32 v163, v177
	v_readlane_b32 s5, v252, 41
	v_lshlrev_b32_e32 v176, 1, v178
	v_lshlrev_b32_e32 v13, 2, v178
	v_lshl_add_u64 v[6:7], s[4:5], 0, v[162:163]
	v_lshl_add_u64 v[6:7], v[6:7], 0, v[176:177]
	global_load_dwordx2 v[14:15], v[6:7], off
	global_load_dwordx2 v[102:103], v[6:7], off offset:16
	global_load_dwordx2 v[104:105], v[6:7], off offset:32
	global_load_dwordx2 v[106:107], v[6:7], off offset:48
	global_load_dwordx2 v[108:109], v[6:7], off offset:64
	global_load_dwordx2 v[110:111], v[6:7], off offset:80
	global_load_dwordx2 v[112:113], v[6:7], off offset:96
	global_load_dwordx2 v[114:115], v[6:7], off offset:112
	global_load_dwordx2 v[116:117], v[6:7], off offset:128
	global_load_dwordx2 v[118:119], v[6:7], off offset:144
	global_load_dwordx2 v[120:121], v[6:7], off offset:160
	global_load_dwordx2 v[122:123], v[6:7], off offset:176
	global_load_dwordx2 v[124:125], v[6:7], off offset:192
	global_load_dwordx2 v[126:127], v[6:7], off offset:208
	global_load_dwordx2 v[128:129], v[6:7], off offset:224
	global_load_dwordx2 v[130:131], v[6:7], off offset:240
	v_readlane_b32 s4, v252, 1
	v_readlane_b32 s5, v252, 2
	s_load_dwordx8 s[12:19], s[4:5], 0x70
	v_add_f32_e32 v12, v4, v5
	s_mov_b32 s2, 0x800000
	v_fmamk_f32 v12, v12, 0x3c000000, v196
	v_mul_f32_e32 v46, 0x4b800000, v12
	s_waitcnt lgkmcnt(0)
	global_load_dwordx4 v[28:31], v13, s[12:13]
	global_load_dwordx4 v[78:81], v13, s[12:13] offset:32
	v_cmp_gt_f32_e32 vcc, s2, v12
	v_readlane_b32 s4, v252, 42
	v_lshlrev_b32_e32 v4, 12, v174
	v_cndmask_b32_e32 v12, v12, v46, vcc
	v_rsq_f32_e32 v12, v12
	v_mov_b32_e32 v5, v177
	v_readlane_b32 s5, v252, 43
	v_mul_f32_e32 v46, 0x45800000, v12
	v_cndmask_b32_e32 v12, v12, v46, vcc
	v_mul_f32_e32 v12, 0x3f4ccccd, v12
	v_pk_mul_f32 v[46:47], v[74:75], v[12:13] op_sel_hi:[1,0]
	v_pk_mul_f32 v[74:75], v[76:77], v[12:13] op_sel_hi:[1,0]
	v_lshl_add_u64 v[4:5], s[4:5], 0, v[4:5]
	v_lshl_add_u64 v[4:5], v[4:5], 0, v[176:177]
	v_pk_mul_f32 v[42:43], v[42:43], v[12:13] op_sel_hi:[1,0]
	v_pk_mul_f32 v[40:41], v[40:41], v[12:13] op_sel_hi:[1,0]
	v_pk_mul_f32 v[34:35], v[34:35], v[12:13] op_sel_hi:[1,0]
	v_pk_mul_f32 v[32:33], v[32:33], v[12:13] op_sel_hi:[1,0]
	v_pk_mul_f32 v[26:27], v[26:27], v[12:13] op_sel_hi:[1,0]
	v_pk_mul_f32 v[24:25], v[24:25], v[12:13] op_sel_hi:[1,0]
	v_pk_mul_f32 v[22:23], v[22:23], v[12:13] op_sel_hi:[1,0]
	v_pk_mul_f32 v[20:21], v[20:21], v[12:13] op_sel_hi:[1,0]
	v_pk_mul_f32 v[18:19], v[18:19], v[12:13] op_sel_hi:[1,0]
	v_pk_mul_f32 v[16:17], v[16:17], v[12:13] op_sel_hi:[1,0]
	v_pk_mul_f32 v[8:9], v[8:9], v[12:13] op_sel_hi:[1,0]
	v_pk_mul_f32 v[10:11], v[10:11], v[12:13] op_sel_hi:[1,0]
	s_waitcnt vmcnt(0)
	v_lshlrev_b32_e32 v82, 16, v14
	v_and_b32_e32 v83, 0xffff0000, v14
	v_lshlrev_b32_e32 v84, 16, v15
	v_and_b32_e32 v85, 0xffff0000, v15
	v_mul_f32_e32 v14, 0xbfb8aa3b, v82
	v_mul_f32_e32 v15, 0xbfb8aa3b, v83
	v_exp_f32_e32 v14, v14
	v_exp_f32_e32 v15, v15
	v_mul_f32_e32 v76, 0xbfb8aa3b, v84
	v_mul_f32_e32 v77, 0xbfb8aa3b, v85
	v_exp_f32_e32 v76, v76
	v_exp_f32_e32 v77, v77
	v_pk_add_f32 v[14:15], v[14:15], 1.0 op_sel_hi:[1,0]
	v_pk_mul_f32 v[30:31], v[74:75], v[30:31]
	v_div_scale_f32 v74, s[4:5], v15, v15, v83
	v_pk_mul_f32 v[28:29], v[46:47], v[28:29]
	v_pk_add_f32 v[46:47], v[76:77], 1.0 op_sel_hi:[1,0]
	v_div_scale_f32 v76, s[4:5], v14, v14, v82
	v_rcp_f32_e32 v90, v74
	v_div_scale_f32 v86, s[6:7], v47, v47, v85
	v_rcp_f32_e32 v91, v76
	v_div_scale_f32 v88, s[8:9], v46, v46, v84
	v_rcp_f32_e32 v92, v86
	v_rcp_f32_e32 v93, v88
	v_fma_f32 v94, -v74, v90, 1.0
	v_div_scale_f32 v75, vcc, v83, v15, v83
	v_fma_f32 v95, -v76, v91, 1.0
	v_fmac_f32_e32 v90, v94, v90
	v_div_scale_f32 v77, s[4:5], v82, v14, v82
	v_fma_f32 v96, -v86, v92, 1.0
	v_fmac_f32_e32 v91, v95, v91
	v_mul_f32_e32 v94, v75, v90
	v_div_scale_f32 v87, s[6:7], v85, v47, v85
	v_fma_f32 v97, -v88, v93, 1.0
	v_fmac_f32_e32 v92, v96, v92
	v_mul_f32_e32 v95, v77, v91
	v_fma_f32 v98, -v74, v94, v75
	v_div_scale_f32 v89, s[8:9], v84, v46, v84
	v_fmac_f32_e32 v93, v97, v93
	v_mul_f32_e32 v96, v87, v92
	v_fma_f32 v99, -v76, v95, v77
	v_fmac_f32_e32 v94, v98, v90
	v_mul_f32_e32 v97, v89, v93
	v_fma_f32 v100, -v86, v96, v87
	v_fmac_f32_e32 v95, v99, v91
	v_fma_f32 v74, -v74, v94, v75
	v_fma_f32 v101, -v88, v97, v89
	v_fmac_f32_e32 v96, v100, v92
	v_fma_f32 v75, -v76, v95, v77
	v_div_fmas_f32 v74, v74, v90, v94
	s_mov_b64 vcc, s[4:5]
	v_fmac_f32_e32 v97, v101, v93
	v_fma_f32 v76, -v86, v96, v87
	v_div_fixup_f32 v15, v74, v15, v83
	v_div_fmas_f32 v74, v75, v91, v95
	s_mov_b64 vcc, s[6:7]
	v_fma_f32 v77, -v88, v97, v89
	v_div_fixup_f32 v14, v74, v14, v82
	v_div_fmas_f32 v74, v76, v92, v96
	s_mov_b64 vcc, s[8:9]
	v_pk_mul_f32 v[14:15], v[28:29], v[14:15]
	v_div_fmas_f32 v28, v77, v93, v97
	v_div_fixup_f32 v29, v74, v47, v85
	v_div_fixup_f32 v28, v28, v46, v84
	v_pk_mul_f32 v[28:29], v[30:31], v[28:29]
	v_cvt_pk_bf16_f32 v14, v14, v15
	v_cvt_pk_bf16_f32 v15, v28, v29
	global_store_dwordx2 v[4:5], v[14:15], off
	v_mov_b32_e32 v14, v102
	v_mov_b32_e32 v15, v103
	v_pk_mul_f32 v[30:31], v[70:71], v[12:13] op_sel_hi:[1,0]
	v_pk_mul_f32 v[28:29], v[72:73], v[12:13] op_sel_hi:[1,0]
	v_pk_mul_f32 v[30:31], v[30:31], v[80:81]
	v_pk_mul_f32 v[28:29], v[28:29], v[78:79]
	v_lshlrev_b32_e32 v70, 16, v14
	v_and_b32_e32 v71, 0xffff0000, v14
	v_lshlrev_b32_e32 v72, 16, v15
	v_and_b32_e32 v73, 0xffff0000, v15
	v_mul_f32_e32 v14, 0xbfb8aa3b, v70
	v_mul_f32_e32 v15, 0xbfb8aa3b, v71
	v_exp_f32_e32 v14, v14
	v_exp_f32_e32 v15, v15
	v_mul_f32_e32 v46, 0xbfb8aa3b, v72
	v_mul_f32_e32 v47, 0xbfb8aa3b, v73
	v_exp_f32_e32 v46, v46
	v_exp_f32_e32 v47, v47
; __device__ __forceinline__ unsigned cvtpk(float lo, float hi) { f32x2 v = {lo, hi}; bf16x2_t b = __builtin_convertvector(v, bf16x2_t); return __builtin_bit_cast(unsigned, b); }
; __device__ __forceinline__ float bf2f(unsigned u16) { return __uint_as_float(u16 << 16); }
; __device__ __forceinline__ float silu(float g) { return g / (1.f + __expf(-g)); }
; template <int MODE>
; __device__ __forceinline__ void attn_unit(const UnitP& P, ALAS char* lds, const float* __restrict__ sub_gain, const int wv0, unsigned& hgen, unsigned* qctr, const int xcd) {
;     ...
;                 for (int d0 = 0; d0 < 4; ++d0)
; #pragma unroll
;                     for (int g = 0; g < 4; ++g) {
;                         const u32x2 gg = *(const u32x2*)(gp + 32 * d0 + 8 * g);
;                         const f32x4 sg = *(const f32x4*)(sub_gain + 32 * d0 + 8 * g + 4 * hi);
;                         const float y0 = o[d0][4 * g + 0] * rn * sg[0] * silu(bf2f(gg.x & 0xffffu)), y1 = o[d0][4 * g + 1] * rn * sg[1] * silu(bf2f(gg.x >> 16));
;                         const float y2 = o[d0][4 * g + 2] * rn * sg[2] * silu(bf2f(gg.y & 0xffffu)), y3 = o[d0][4 * g + 3] * rn * sg[3] * silu(bf2f(gg.y >> 16));
;                         u32x2 w; w.x = cvtpk(y0, y1); w.y = cvtpk(y2, y3);
;                         *(u32x2*)(mp + 32 * d0 + 8 * g) = w;
	v_pk_add_f32 v[14:15], v[14:15], 1.0 op_sel_hi:[1,0]
	v_pk_add_f32 v[46:47], v[46:47], 1.0 op_sel_hi:[1,0]
	v_div_scale_f32 v74, s[4:5], v15, v15, v71
	v_div_scale_f32 v76, s[4:5], v14, v14, v70
	v_rcp_f32_e32 v82, v74
	v_div_scale_f32 v78, s[6:7], v47, v47, v73
	v_rcp_f32_e32 v83, v76
	v_div_scale_f32 v80, s[8:9], v46, v46, v72
	v_rcp_f32_e32 v84, v78
	v_rcp_f32_e32 v85, v80
	v_fma_f32 v86, -v74, v82, 1.0
	v_div_scale_f32 v75, vcc, v71, v15, v71
	v_fma_f32 v87, -v76, v83, 1.0
	v_fmac_f32_e32 v82, v86, v82
	v_div_scale_f32 v77, s[4:5], v70, v14, v70
	v_fma_f32 v88, -v78, v84, 1.0
	v_fmac_f32_e32 v83, v87, v83
	v_mul_f32_e32 v86, v75, v82
	v_div_scale_f32 v79, s[6:7], v73, v47, v73
	v_fma_f32 v89, -v80, v85, 1.0
	v_fmac_f32_e32 v84, v88, v84
	v_mul_f32_e32 v87, v77, v83
	v_fma_f32 v90, -v74, v86, v75
	v_div_scale_f32 v81, s[8:9], v72, v46, v72
	v_fmac_f32_e32 v85, v89, v85
	v_mul_f32_e32 v88, v79, v84
	v_fma_f32 v91, -v76, v87, v77
	v_fmac_f32_e32 v86, v90, v82
	v_mul_f32_e32 v89, v81, v85
	v_fma_f32 v92, -v78, v88, v79
	v_fmac_f32_e32 v87, v91, v83
	v_fma_f32 v74, -v74, v86, v75
	v_fma_f32 v93, -v80, v89, v81
	v_fmac_f32_e32 v88, v92, v84
	v_fma_f32 v75, -v76, v87, v77
	v_div_fmas_f32 v74, v74, v82, v86
	s_mov_b64 vcc, s[4:5]
	v_fmac_f32_e32 v89, v93, v85
	v_fma_f32 v76, -v78, v88, v79
	v_div_fixup_f32 v15, v74, v15, v71
	v_div_fmas_f32 v71, v75, v83, v87
	s_mov_b64 vcc, s[6:7]
	v_fma_f32 v77, -v80, v89, v81
	v_div_fixup_f32 v14, v71, v14, v70
	v_div_fmas_f32 v70, v76, v84, v88
	s_mov_b64 vcc, s[8:9]
	v_pk_mul_f32 v[14:15], v[28:29], v[14:15]
	v_div_fmas_f32 v28, v77, v85, v89
	v_div_fixup_f32 v29, v70, v47, v73
	v_div_fixup_f32 v28, v28, v46, v72
	v_pk_mul_f32 v[28:29], v[30:31], v[28:29]
	v_cvt_pk_bf16_f32 v14, v14, v15
	v_cvt_pk_bf16_f32 v15, v28, v29
	global_store_dwordx2 v[4:5], v[14:15], off offset:16
	v_mov_b32_e32 v14, v104
	v_mov_b32_e32 v15, v105
	s_nop 0
	global_load_dwordx4 v[28:31], v13, s[12:13] offset:64
	global_load_dwordx4 v[70:73], v13, s[12:13] offset:96
	v_pk_mul_f32 v[46:47], v[66:67], v[12:13] op_sel_hi:[1,0]
	v_pk_mul_f32 v[66:67], v[68:69], v[12:13] op_sel_hi:[1,0]
	v_lshlrev_b32_e32 v74, 16, v14
	v_and_b32_e32 v75, 0xffff0000, v14
	v_lshlrev_b32_e32 v76, 16, v15
	v_and_b32_e32 v77, 0xffff0000, v15
	v_mul_f32_e32 v14, 0xbfb8aa3b, v74
	v_mul_f32_e32 v15, 0xbfb8aa3b, v75
	v_exp_f32_e32 v14, v14
	v_exp_f32_e32 v15, v15
	v_mul_f32_e32 v68, 0xbfb8aa3b, v76
	v_mul_f32_e32 v69, 0xbfb8aa3b, v77
	v_exp_f32_e32 v68, v68
	v_exp_f32_e32 v69, v69
	v_pk_add_f32 v[14:15], v[14:15], 1.0 op_sel_hi:[1,0]
	s_waitcnt vmcnt(1)
	v_pk_mul_f32 v[30:31], v[66:67], v[30:31]
	v_div_scale_f32 v66, s[4:5], v15, v15, v75
	v_pk_mul_f32 v[28:29], v[46:47], v[28:29]
	v_pk_add_f32 v[46:47], v[68:69], 1.0 op_sel_hi:[1,0]
	v_div_scale_f32 v68, s[4:5], v14, v14, v74
	v_rcp_f32_e32 v82, v66
	v_div_scale_f32 v78, s[6:7], v47, v47, v77
	v_rcp_f32_e32 v83, v68
	v_div_scale_f32 v80, s[8:9], v46, v46, v76
	v_rcp_f32_e32 v84, v78
	v_rcp_f32_e32 v85, v80
	v_fma_f32 v86, -v66, v82, 1.0
	v_div_scale_f32 v67, vcc, v75, v15, v75
	v_fma_f32 v87, -v68, v83, 1.0
	v_fmac_f32_e32 v82, v86, v82
	v_div_scale_f32 v69, s[4:5], v74, v14, v74
	v_fma_f32 v88, -v78, v84, 1.0
	v_fmac_f32_e32 v83, v87, v83
	v_mul_f32_e32 v86, v67, v82
	v_div_scale_f32 v79, s[6:7], v77, v47, v77
	v_fma_f32 v89, -v80, v85, 1.0
	v_fmac_f32_e32 v84, v88, v84
	v_mul_f32_e32 v87, v69, v83
	v_fma_f32 v90, -v66, v86, v67
	v_div_scale_f32 v81, s[8:9], v76, v46, v76
	v_fmac_f32_e32 v85, v89, v85
	v_mul_f32_e32 v88, v79, v84
	v_fma_f32 v91, -v68, v87, v69
	v_fmac_f32_e32 v86, v90, v82
	v_mul_f32_e32 v89, v81, v85
	v_fma_f32 v92, -v78, v88, v79
	v_fmac_f32_e32 v87, v91, v83
	v_fma_f32 v66, -v66, v86, v67
	v_fma_f32 v93, -v80, v89, v81
	v_fmac_f32_e32 v88, v92, v84
	v_fma_f32 v67, -v68, v87, v69
	v_div_fmas_f32 v66, v66, v82, v86
	s_mov_b64 vcc, s[4:5]
	v_fmac_f32_e32 v89, v93, v85
	v_fma_f32 v68, -v78, v88, v79
	v_div_fixup_f32 v15, v66, v15, v75
	v_div_fmas_f32 v66, v67, v83, v87
	s_mov_b64 vcc, s[6:7]
	v_fma_f32 v69, -v80, v89, v81
	v_div_fixup_f32 v14, v66, v14, v74
	v_div_fmas_f32 v66, v68, v84, v88
	s_mov_b64 vcc, s[8:9]
	v_pk_mul_f32 v[14:15], v[28:29], v[14:15]
	v_div_fmas_f32 v28, v69, v85, v89
	v_div_fixup_f32 v29, v66, v47, v77
	v_div_fixup_f32 v28, v28, v46, v76
	v_pk_mul_f32 v[28:29], v[30:31], v[28:29]
	v_cvt_pk_bf16_f32 v14, v14, v15
	v_cvt_pk_bf16_f32 v15, v28, v29
	global_store_dwordx2 v[4:5], v[14:15], off offset:32
	v_mov_b32_e32 v14, v106
	v_mov_b32_e32 v15, v107
	v_pk_mul_f32 v[30:31], v[62:63], v[12:13] op_sel_hi:[1,0]
	v_pk_mul_f32 v[28:29], v[64:65], v[12:13] op_sel_hi:[1,0]
	s_waitcnt vmcnt(1)
; __device__ __forceinline__ unsigned cvtpk(float lo, float hi) { f32x2 v = {lo, hi}; bf16x2_t b = __builtin_convertvector(v, bf16x2_t); return __builtin_bit_cast(unsigned, b); }
; __device__ __forceinline__ float bf2f(unsigned u16) { return __uint_as_float(u16 << 16); }
; __device__ __forceinline__ float silu(float g) { return g / (1.f + __expf(-g)); }
; template <int MODE>
; __device__ __forceinline__ void attn_unit(const UnitP& P, ALAS char* lds, const float* __restrict__ sub_gain, const int wv0, unsigned& hgen, unsigned* qctr, const int xcd) {
;     ...
;                 for (int d0 = 0; d0 < 4; ++d0)
; #pragma unroll
;                     for (int g = 0; g < 4; ++g) {
;                         const u32x2 gg = *(const u32x2*)(gp + 32 * d0 + 8 * g);
;                         const f32x4 sg = *(const f32x4*)(sub_gain + 32 * d0 + 8 * g + 4 * hi);
;                         const float y0 = o[d0][4 * g + 0] * rn * sg[0] * silu(bf2f(gg.x & 0xffffu)), y1 = o[d0][4 * g + 1] * rn * sg[1] * silu(bf2f(gg.x >> 16));
;                         const float y2 = o[d0][4 * g + 2] * rn * sg[2] * silu(bf2f(gg.y & 0xffffu)), y3 = o[d0][4 * g + 3] * rn * sg[3] * silu(bf2f(gg.y >> 16));
;                         u32x2 w; w.x = cvtpk(y0, y1); w.y = cvtpk(y2, y3);
;                         *(u32x2*)(mp + 32 * d0 + 8 * g) = w;
	v_pk_mul_f32 v[30:31], v[30:31], v[72:73]
	v_pk_mul_f32 v[28:29], v[28:29], v[70:71]
	v_lshlrev_b32_e32 v62, 16, v14
	v_and_b32_e32 v63, 0xffff0000, v14
	v_lshlrev_b32_e32 v64, 16, v15
	v_and_b32_e32 v65, 0xffff0000, v15
	v_mul_f32_e32 v14, 0xbfb8aa3b, v62
	v_mul_f32_e32 v15, 0xbfb8aa3b, v63
	v_exp_f32_e32 v14, v14
	v_exp_f32_e32 v15, v15
	v_mul_f32_e32 v46, 0xbfb8aa3b, v64
	v_mul_f32_e32 v47, 0xbfb8aa3b, v65
	v_exp_f32_e32 v46, v46
	v_exp_f32_e32 v47, v47
	v_pk_add_f32 v[14:15], v[14:15], 1.0 op_sel_hi:[1,0]
	v_pk_add_f32 v[46:47], v[46:47], 1.0 op_sel_hi:[1,0]
	v_div_scale_f32 v66, s[4:5], v15, v15, v63
	v_div_scale_f32 v68, s[4:5], v14, v14, v62
	v_rcp_f32_e32 v74, v66
	v_div_scale_f32 v70, s[6:7], v47, v47, v65
	v_rcp_f32_e32 v75, v68
	v_div_scale_f32 v72, s[8:9], v46, v46, v64
	v_rcp_f32_e32 v76, v70
	v_rcp_f32_e32 v77, v72
	v_fma_f32 v78, -v66, v74, 1.0
	v_div_scale_f32 v67, vcc, v63, v15, v63
	v_fma_f32 v79, -v68, v75, 1.0
	v_fmac_f32_e32 v74, v78, v74
	v_div_scale_f32 v69, s[4:5], v62, v14, v62
	v_fma_f32 v80, -v70, v76, 1.0
	v_fmac_f32_e32 v75, v79, v75
	v_mul_f32_e32 v78, v67, v74
	v_div_scale_f32 v71, s[6:7], v65, v47, v65
	v_fma_f32 v81, -v72, v77, 1.0
	v_fmac_f32_e32 v76, v80, v76
	v_mul_f32_e32 v79, v69, v75
	v_fma_f32 v82, -v66, v78, v67
	v_div_scale_f32 v73, s[8:9], v64, v46, v64
	v_fmac_f32_e32 v77, v81, v77
	v_mul_f32_e32 v80, v71, v76
	v_fma_f32 v83, -v68, v79, v69
	v_fmac_f32_e32 v78, v82, v74
	v_mul_f32_e32 v81, v73, v77
	v_fma_f32 v84, -v70, v80, v71
	v_fmac_f32_e32 v79, v83, v75
	v_fma_f32 v66, -v66, v78, v67
	v_fma_f32 v85, -v72, v81, v73
	v_fmac_f32_e32 v80, v84, v76
	v_fma_f32 v67, -v68, v79, v69
	v_div_fmas_f32 v66, v66, v74, v78
	s_mov_b64 vcc, s[4:5]
	v_fmac_f32_e32 v81, v85, v77
	v_fma_f32 v68, -v70, v80, v71
	v_div_fixup_f32 v15, v66, v15, v63
	v_div_fmas_f32 v63, v67, v75, v79
	s_mov_b64 vcc, s[6:7]
	v_fma_f32 v69, -v72, v81, v73
	v_div_fixup_f32 v14, v63, v14, v62
	v_div_fmas_f32 v62, v68, v76, v80
	s_mov_b64 vcc, s[8:9]
	v_pk_mul_f32 v[14:15], v[28:29], v[14:15]
	v_div_fmas_f32 v28, v69, v77, v81
	v_div_fixup_f32 v29, v62, v47, v65
	v_div_fixup_f32 v28, v28, v46, v64
	v_pk_mul_f32 v[28:29], v[30:31], v[28:29]
	v_cvt_pk_bf16_f32 v14, v14, v15
	v_cvt_pk_bf16_f32 v15, v28, v29
	global_store_dwordx2 v[4:5], v[14:15], off offset:48
	v_mov_b32_e32 v14, v108
	v_mov_b32_e32 v15, v109
	s_nop 0
	global_load_dwordx4 v[28:31], v13, s[12:13] offset:128
	global_load_dwordx4 v[62:65], v13, s[12:13] offset:160
	v_pk_mul_f32 v[46:47], v[58:59], v[12:13] op_sel_hi:[1,0]
	v_pk_mul_f32 v[58:59], v[60:61], v[12:13] op_sel_hi:[1,0]
	v_lshlrev_b32_e32 v66, 16, v14
	v_and_b32_e32 v67, 0xffff0000, v14
	v_lshlrev_b32_e32 v68, 16, v15
	v_and_b32_e32 v69, 0xffff0000, v15
	v_mul_f32_e32 v14, 0xbfb8aa3b, v66
	v_mul_f32_e32 v15, 0xbfb8aa3b, v67
	v_exp_f32_e32 v14, v14
	v_exp_f32_e32 v15, v15
	v_mul_f32_e32 v60, 0xbfb8aa3b, v68
	v_mul_f32_e32 v61, 0xbfb8aa3b, v69
	v_exp_f32_e32 v60, v60
	v_exp_f32_e32 v61, v61
	v_pk_add_f32 v[14:15], v[14:15], 1.0 op_sel_hi:[1,0]
	s_waitcnt vmcnt(1)
	v_pk_mul_f32 v[30:31], v[58:59], v[30:31]
	v_div_scale_f32 v58, s[4:5], v15, v15, v67
	v_pk_mul_f32 v[28:29], v[46:47], v[28:29]
	v_pk_add_f32 v[46:47], v[60:61], 1.0 op_sel_hi:[1,0]
	v_div_scale_f32 v60, s[4:5], v14, v14, v66
	v_rcp_f32_e32 v74, v58
	v_div_scale_f32 v70, s[6:7], v47, v47, v69
	v_rcp_f32_e32 v75, v60
	v_div_scale_f32 v72, s[8:9], v46, v46, v68
	v_rcp_f32_e32 v76, v70
	v_rcp_f32_e32 v77, v72
	v_fma_f32 v78, -v58, v74, 1.0
	v_div_scale_f32 v59, vcc, v67, v15, v67
	v_fma_f32 v79, -v60, v75, 1.0
	v_fmac_f32_e32 v74, v78, v74
	v_div_scale_f32 v61, s[4:5], v66, v14, v66
	v_fma_f32 v80, -v70, v76, 1.0
	v_fmac_f32_e32 v75, v79, v75
	v_mul_f32_e32 v78, v59, v74
	v_div_scale_f32 v71, s[6:7], v69, v47, v69
	v_fma_f32 v81, -v72, v77, 1.0
	v_fmac_f32_e32 v76, v80, v76
	v_mul_f32_e32 v79, v61, v75
	v_fma_f32 v82, -v58, v78, v59
	v_div_scale_f32 v73, s[8:9], v68, v46, v68
	v_fmac_f32_e32 v77, v81, v77
	v_mul_f32_e32 v80, v71, v76
	v_fma_f32 v83, -v60, v79, v61
	v_fmac_f32_e32 v78, v82, v74
	v_mul_f32_e32 v81, v73, v77
	v_fma_f32 v84, -v70, v80, v71
	v_fmac_f32_e32 v79, v83, v75
	v_fma_f32 v58, -v58, v78, v59
	v_fma_f32 v85, -v72, v81, v73
	v_fmac_f32_e32 v80, v84, v76
	v_fma_f32 v59, -v60, v79, v61
	v_div_fmas_f32 v58, v58, v74, v78
	s_mov_b64 vcc, s[4:5]
	v_fmac_f32_e32 v81, v85, v77
	v_fma_f32 v60, -v70, v80, v71
	v_div_fixup_f32 v15, v58, v15, v67
	v_div_fmas_f32 v58, v59, v75, v79
	s_mov_b64 vcc, s[6:7]
	v_fma_f32 v61, -v72, v81, v73
	v_div_fixup_f32 v14, v58, v14, v66
	v_div_fmas_f32 v58, v60, v76, v80
	s_mov_b64 vcc, s[8:9]
	v_pk_mul_f32 v[14:15], v[28:29], v[14:15]
	v_div_fmas_f32 v28, v61, v77, v81
	v_div_fixup_f32 v29, v58, v47, v69
	v_div_fixup_f32 v28, v28, v46, v68
	v_pk_mul_f32 v[28:29], v[30:31], v[28:29]
	v_cvt_pk_bf16_f32 v14, v14, v15
	v_cvt_pk_bf16_f32 v15, v28, v29
	global_store_dwordx2 v[4:5], v[14:15], off offset:64
	v_mov_b32_e32 v14, v110
	v_mov_b32_e32 v15, v111
	v_pk_mul_f32 v[30:31], v[54:55], v[12:13] op_sel_hi:[1,0]
	v_pk_mul_f32 v[28:29], v[56:57], v[12:13] op_sel_hi:[1,0]
	s_waitcnt vmcnt(1)
; __device__ __forceinline__ unsigned cvtpk(float lo, float hi) { f32x2 v = {lo, hi}; bf16x2_t b = __builtin_convertvector(v, bf16x2_t); return __builtin_bit_cast(unsigned, b); }
; __device__ __forceinline__ float bf2f(unsigned u16) { return __uint_as_float(u16 << 16); }
; __device__ __forceinline__ float silu(float g) { return g / (1.f + __expf(-g)); }
; template <int MODE>
; __device__ __forceinline__ void attn_unit(const UnitP& P, ALAS char* lds, const float* __restrict__ sub_gain, const int wv0, unsigned& hgen, unsigned* qctr, const int xcd) {
;     ...
;                 for (int d0 = 0; d0 < 4; ++d0)
; #pragma unroll
;                     for (int g = 0; g < 4; ++g) {
;                         const u32x2 gg = *(const u32x2*)(gp + 32 * d0 + 8 * g);
;                         const f32x4 sg = *(const f32x4*)(sub_gain + 32 * d0 + 8 * g + 4 * hi);
;                         const float y0 = o[d0][4 * g + 0] * rn * sg[0] * silu(bf2f(gg.x & 0xffffu)), y1 = o[d0][4 * g + 1] * rn * sg[1] * silu(bf2f(gg.x >> 16));
;                         const float y2 = o[d0][4 * g + 2] * rn * sg[2] * silu(bf2f(gg.y & 0xffffu)), y3 = o[d0][4 * g + 3] * rn * sg[3] * silu(bf2f(gg.y >> 16));
;                         u32x2 w; w.x = cvtpk(y0, y1); w.y = cvtpk(y2, y3);
;                         *(u32x2*)(mp + 32 * d0 + 8 * g) = w;
	v_pk_mul_f32 v[30:31], v[30:31], v[64:65]
	v_pk_mul_f32 v[28:29], v[28:29], v[62:63]
	v_lshlrev_b32_e32 v54, 16, v14
	v_and_b32_e32 v55, 0xffff0000, v14
	v_lshlrev_b32_e32 v56, 16, v15
	v_and_b32_e32 v57, 0xffff0000, v15
	v_mul_f32_e32 v14, 0xbfb8aa3b, v54
	v_mul_f32_e32 v15, 0xbfb8aa3b, v55
	v_exp_f32_e32 v14, v14
	v_exp_f32_e32 v15, v15
	v_mul_f32_e32 v46, 0xbfb8aa3b, v56
	v_mul_f32_e32 v47, 0xbfb8aa3b, v57
	v_exp_f32_e32 v46, v46
	v_exp_f32_e32 v47, v47
	v_pk_add_f32 v[14:15], v[14:15], 1.0 op_sel_hi:[1,0]
	v_pk_add_f32 v[46:47], v[46:47], 1.0 op_sel_hi:[1,0]
	v_div_scale_f32 v58, s[4:5], v15, v15, v55
	v_div_scale_f32 v60, s[4:5], v14, v14, v54
	v_rcp_f32_e32 v66, v58
	v_div_scale_f32 v62, s[6:7], v47, v47, v57
	v_rcp_f32_e32 v67, v60
	v_div_scale_f32 v64, s[8:9], v46, v46, v56
	v_rcp_f32_e32 v68, v62
	v_rcp_f32_e32 v69, v64
	v_fma_f32 v70, -v58, v66, 1.0
	v_div_scale_f32 v59, vcc, v55, v15, v55
	v_fma_f32 v71, -v60, v67, 1.0
	v_fmac_f32_e32 v66, v70, v66
	v_div_scale_f32 v61, s[4:5], v54, v14, v54
	v_fma_f32 v72, -v62, v68, 1.0
	v_fmac_f32_e32 v67, v71, v67
	v_mul_f32_e32 v70, v59, v66
	v_div_scale_f32 v63, s[6:7], v57, v47, v57
	v_fma_f32 v73, -v64, v69, 1.0
	v_fmac_f32_e32 v68, v72, v68
	v_mul_f32_e32 v71, v61, v67
	v_fma_f32 v74, -v58, v70, v59
	v_div_scale_f32 v65, s[8:9], v56, v46, v56
	v_fmac_f32_e32 v69, v73, v69
	v_mul_f32_e32 v72, v63, v68
	v_fma_f32 v75, -v60, v71, v61
	v_fmac_f32_e32 v70, v74, v66
	v_mul_f32_e32 v73, v65, v69
	v_fma_f32 v76, -v62, v72, v63
	v_fmac_f32_e32 v71, v75, v67
	v_fma_f32 v58, -v58, v70, v59
	v_fma_f32 v77, -v64, v73, v65
	v_fmac_f32_e32 v72, v76, v68
	v_fma_f32 v59, -v60, v71, v61
	v_div_fmas_f32 v58, v58, v66, v70
	s_mov_b64 vcc, s[4:5]
	v_fmac_f32_e32 v73, v77, v69
	v_fma_f32 v60, -v62, v72, v63
	v_div_fixup_f32 v15, v58, v15, v55
	v_div_fmas_f32 v55, v59, v67, v71
	s_mov_b64 vcc, s[6:7]
	v_fma_f32 v61, -v64, v73, v65
	v_div_fixup_f32 v14, v55, v14, v54
	v_div_fmas_f32 v54, v60, v68, v72
	s_mov_b64 vcc, s[8:9]
	v_pk_mul_f32 v[14:15], v[28:29], v[14:15]
	v_div_fmas_f32 v28, v61, v69, v73
	v_div_fixup_f32 v29, v54, v47, v57
	v_div_fixup_f32 v28, v28, v46, v56
	v_pk_mul_f32 v[28:29], v[30:31], v[28:29]
	v_cvt_pk_bf16_f32 v14, v14, v15
	v_cvt_pk_bf16_f32 v15, v28, v29
	global_store_dwordx2 v[4:5], v[14:15], off offset:80
	v_mov_b32_e32 v14, v112
	v_mov_b32_e32 v15, v113
	s_nop 0
	global_load_dwordx4 v[28:31], v13, s[12:13] offset:192
	global_load_dwordx4 v[54:57], v13, s[12:13] offset:224
	v_pk_mul_f32 v[46:47], v[50:51], v[12:13] op_sel_hi:[1,0]
	v_pk_mul_f32 v[50:51], v[52:53], v[12:13] op_sel_hi:[1,0]
	v_lshlrev_b32_e32 v58, 16, v14
	v_and_b32_e32 v59, 0xffff0000, v14
	v_lshlrev_b32_e32 v60, 16, v15
	v_and_b32_e32 v61, 0xffff0000, v15
	v_mul_f32_e32 v14, 0xbfb8aa3b, v58
	v_mul_f32_e32 v15, 0xbfb8aa3b, v59
	v_exp_f32_e32 v14, v14
	v_exp_f32_e32 v15, v15
	v_mul_f32_e32 v52, 0xbfb8aa3b, v60
	v_mul_f32_e32 v53, 0xbfb8aa3b, v61
	v_exp_f32_e32 v52, v52
	v_exp_f32_e32 v53, v53
	v_pk_add_f32 v[14:15], v[14:15], 1.0 op_sel_hi:[1,0]
	s_waitcnt vmcnt(1)
	v_pk_mul_f32 v[30:31], v[50:51], v[30:31]
	v_div_scale_f32 v50, s[4:5], v15, v15, v59
	v_pk_mul_f32 v[28:29], v[46:47], v[28:29]
	v_pk_add_f32 v[46:47], v[52:53], 1.0 op_sel_hi:[1,0]
	v_div_scale_f32 v52, s[4:5], v14, v14, v58
	v_rcp_f32_e32 v66, v50
	v_div_scale_f32 v62, s[6:7], v47, v47, v61
	v_rcp_f32_e32 v67, v52
	v_div_scale_f32 v64, s[8:9], v46, v46, v60
	v_rcp_f32_e32 v68, v62
	v_rcp_f32_e32 v69, v64
	v_fma_f32 v70, -v50, v66, 1.0
	v_div_scale_f32 v51, vcc, v59, v15, v59
	v_fma_f32 v71, -v52, v67, 1.0
	v_fmac_f32_e32 v66, v70, v66
	v_div_scale_f32 v53, s[4:5], v58, v14, v58
	v_fma_f32 v72, -v62, v68, 1.0
	v_fmac_f32_e32 v67, v71, v67
	v_mul_f32_e32 v70, v51, v66
	v_div_scale_f32 v63, s[6:7], v61, v47, v61
	v_fma_f32 v73, -v64, v69, 1.0
	v_fmac_f32_e32 v68, v72, v68
	v_mul_f32_e32 v71, v53, v67
	v_fma_f32 v74, -v50, v70, v51
	v_div_scale_f32 v65, s[8:9], v60, v46, v60
	v_fmac_f32_e32 v69, v73, v69
	v_mul_f32_e32 v72, v63, v68
	v_fma_f32 v75, -v52, v71, v53
	v_fmac_f32_e32 v70, v74, v66
	v_mul_f32_e32 v73, v65, v69
	v_fma_f32 v76, -v62, v72, v63
	v_fmac_f32_e32 v71, v75, v67
	v_fma_f32 v50, -v50, v70, v51
	v_fma_f32 v77, -v64, v73, v65
	v_fmac_f32_e32 v72, v76, v68
	v_fma_f32 v51, -v52, v71, v53
	v_div_fmas_f32 v50, v50, v66, v70
	s_mov_b64 vcc, s[4:5]
	v_fmac_f32_e32 v73, v77, v69
	v_fma_f32 v52, -v62, v72, v63
	v_div_fixup_f32 v15, v50, v15, v59
	v_div_fmas_f32 v50, v51, v67, v71
	s_mov_b64 vcc, s[6:7]
	v_fma_f32 v53, -v64, v73, v65
	v_div_fixup_f32 v14, v50, v14, v58
	v_div_fmas_f32 v50, v52, v68, v72
	s_mov_b64 vcc, s[8:9]
	v_pk_mul_f32 v[14:15], v[28:29], v[14:15]
	v_div_fmas_f32 v28, v53, v69, v73
	v_div_fixup_f32 v29, v50, v47, v61
	v_div_fixup_f32 v28, v28, v46, v60
	v_pk_mul_f32 v[28:29], v[30:31], v[28:29]
	v_cvt_pk_bf16_f32 v14, v14, v15
	v_cvt_pk_bf16_f32 v15, v28, v29
	global_store_dwordx2 v[4:5], v[14:15], off offset:96
	v_mov_b32_e32 v14, v114
	v_mov_b32_e32 v15, v115
	v_pk_mul_f32 v[28:29], v[48:49], v[12:13] op_sel_hi:[1,0]
	v_pk_mul_f32 v[30:31], v[44:45], v[12:13] op_sel_hi:[1,0]
	s_waitcnt vmcnt(1)
; __device__ __forceinline__ unsigned cvtpk(float lo, float hi) { f32x2 v = {lo, hi}; bf16x2_t b = __builtin_convertvector(v, bf16x2_t); return __builtin_bit_cast(unsigned, b); }
; __device__ __forceinline__ float bf2f(unsigned u16) { return __uint_as_float(u16 << 16); }
; __device__ __forceinline__ float silu(float g) { return g / (1.f + __expf(-g)); }
; template <int MODE>
; __device__ __forceinline__ void attn_unit(const UnitP& P, ALAS char* lds, const float* __restrict__ sub_gain, const int wv0, unsigned& hgen, unsigned* qctr, const int xcd) {
;     ...
;                 for (int d0 = 0; d0 < 4; ++d0)
; #pragma unroll
;                     for (int g = 0; g < 4; ++g) {
;                         const u32x2 gg = *(const u32x2*)(gp + 32 * d0 + 8 * g);
;                         const f32x4 sg = *(const f32x4*)(sub_gain + 32 * d0 + 8 * g + 4 * hi);
;                         const float y0 = o[d0][4 * g + 0] * rn * sg[0] * silu(bf2f(gg.x & 0xffffu)), y1 = o[d0][4 * g + 1] * rn * sg[1] * silu(bf2f(gg.x >> 16));
;                         const float y2 = o[d0][4 * g + 2] * rn * sg[2] * silu(bf2f(gg.y & 0xffffu)), y3 = o[d0][4 * g + 3] * rn * sg[3] * silu(bf2f(gg.y >> 16));
;                         u32x2 w; w.x = cvtpk(y0, y1); w.y = cvtpk(y2, y3);
;                         *(u32x2*)(mp + 32 * d0 + 8 * g) = w;
	v_pk_mul_f32 v[28:29], v[28:29], v[54:55]
	v_pk_mul_f32 v[30:31], v[30:31], v[56:57]
	v_lshlrev_b32_e32 v46, 16, v14
	v_and_b32_e32 v47, 0xffff0000, v14
	v_lshlrev_b32_e32 v48, 16, v15
	v_and_b32_e32 v49, 0xffff0000, v15
	v_mul_f32_e32 v14, 0xbfb8aa3b, v46
	v_mul_f32_e32 v15, 0xbfb8aa3b, v47
	v_exp_f32_e32 v14, v14
	v_exp_f32_e32 v15, v15
	v_mul_f32_e32 v44, 0xbfb8aa3b, v48
	v_mul_f32_e32 v45, 0xbfb8aa3b, v49
	v_exp_f32_e32 v44, v44
	v_exp_f32_e32 v45, v45
	v_pk_add_f32 v[14:15], v[14:15], 1.0 op_sel_hi:[1,0]
	v_pk_add_f32 v[44:45], v[44:45], 1.0 op_sel_hi:[1,0]
	v_div_scale_f32 v50, s[4:5], v15, v15, v47
	v_div_scale_f32 v52, s[4:5], v14, v14, v46
	v_rcp_f32_e32 v58, v50
	v_div_scale_f32 v54, s[6:7], v45, v45, v49
	v_rcp_f32_e32 v59, v52
	v_div_scale_f32 v56, s[8:9], v44, v44, v48
	v_rcp_f32_e32 v60, v54
	v_rcp_f32_e32 v61, v56
	v_fma_f32 v62, -v50, v58, 1.0
	v_div_scale_f32 v51, vcc, v47, v15, v47
	v_fma_f32 v63, -v52, v59, 1.0
	v_fmac_f32_e32 v58, v62, v58
	v_div_scale_f32 v53, s[4:5], v46, v14, v46
	v_fma_f32 v64, -v54, v60, 1.0
	v_fmac_f32_e32 v59, v63, v59
	v_mul_f32_e32 v62, v51, v58
	v_div_scale_f32 v55, s[6:7], v49, v45, v49
	v_fma_f32 v65, -v56, v61, 1.0
	v_fmac_f32_e32 v60, v64, v60
	v_mul_f32_e32 v63, v53, v59
	v_fma_f32 v66, -v50, v62, v51
	v_div_scale_f32 v57, s[8:9], v48, v44, v48
	v_fmac_f32_e32 v61, v65, v61
	v_mul_f32_e32 v64, v55, v60
	v_fma_f32 v67, -v52, v63, v53
	v_fmac_f32_e32 v62, v66, v58
	v_mul_f32_e32 v65, v57, v61
	v_fma_f32 v68, -v54, v64, v55
	v_fmac_f32_e32 v63, v67, v59
	v_fma_f32 v50, -v50, v62, v51
	v_fma_f32 v69, -v56, v65, v57
	v_fmac_f32_e32 v64, v68, v60
	v_fma_f32 v51, -v52, v63, v53
	v_div_fmas_f32 v50, v50, v58, v62
	s_mov_b64 vcc, s[4:5]
	v_fmac_f32_e32 v65, v69, v61
	v_fma_f32 v52, -v54, v64, v55
	v_div_fixup_f32 v15, v50, v15, v47
	v_div_fmas_f32 v47, v51, v59, v63
	s_mov_b64 vcc, s[6:7]
	v_fma_f32 v53, -v56, v65, v57
	v_div_fixup_f32 v14, v47, v14, v46
	v_div_fmas_f32 v46, v52, v60, v64
	s_mov_b64 vcc, s[8:9]
	v_pk_mul_f32 v[14:15], v[28:29], v[14:15]
	v_div_fmas_f32 v28, v53, v61, v65
	v_div_fixup_f32 v29, v46, v45, v49
	v_div_fixup_f32 v28, v28, v44, v48
	v_pk_mul_f32 v[28:29], v[30:31], v[28:29]
	v_cvt_pk_bf16_f32 v14, v14, v15
	v_cvt_pk_bf16_f32 v15, v28, v29
	global_store_dwordx2 v[4:5], v[14:15], off offset:112
	v_mov_b32_e32 v14, v116
	v_mov_b32_e32 v15, v117
	s_nop 0
	global_load_dwordx4 v[28:31], v13, s[12:13] offset:256
	global_load_dwordx4 v[44:47], v13, s[12:13] offset:288
	v_lshlrev_b32_e32 v50, 16, v14
	v_and_b32_e32 v51, 0xffff0000, v14
	v_lshlrev_b32_e32 v52, 16, v15
	v_and_b32_e32 v53, 0xffff0000, v15
	v_mul_f32_e32 v14, 0xbfb8aa3b, v50
	v_mul_f32_e32 v15, 0xbfb8aa3b, v51
	v_exp_f32_e32 v14, v14
	v_exp_f32_e32 v15, v15
	v_mul_f32_e32 v48, 0xbfb8aa3b, v52
	v_mul_f32_e32 v49, 0xbfb8aa3b, v53
	v_exp_f32_e32 v48, v48
	v_exp_f32_e32 v49, v49
	v_pk_add_f32 v[14:15], v[14:15], 1.0 op_sel_hi:[1,0]
	s_waitcnt vmcnt(1)
	v_pk_mul_f32 v[30:31], v[42:43], v[30:31]
	v_div_scale_f32 v42, s[4:5], v15, v15, v51
	v_pk_mul_f32 v[28:29], v[40:41], v[28:29]
	v_pk_add_f32 v[40:41], v[48:49], 1.0 op_sel_hi:[1,0]
	v_div_scale_f32 v48, s[4:5], v14, v14, v50
	v_rcp_f32_e32 v58, v42
	v_div_scale_f32 v54, s[6:7], v41, v41, v53
	v_rcp_f32_e32 v59, v48
	v_div_scale_f32 v56, s[8:9], v40, v40, v52
	v_rcp_f32_e32 v60, v54
	v_rcp_f32_e32 v61, v56
	v_fma_f32 v62, -v42, v58, 1.0
	v_div_scale_f32 v43, vcc, v51, v15, v51
	v_fma_f32 v63, -v48, v59, 1.0
	v_fmac_f32_e32 v58, v62, v58
	v_div_scale_f32 v49, s[4:5], v50, v14, v50
	v_fma_f32 v64, -v54, v60, 1.0
	v_fmac_f32_e32 v59, v63, v59
	v_mul_f32_e32 v62, v43, v58
	v_div_scale_f32 v55, s[6:7], v53, v41, v53
	v_fma_f32 v65, -v56, v61, 1.0
	v_fmac_f32_e32 v60, v64, v60
	v_mul_f32_e32 v63, v49, v59
	v_fma_f32 v66, -v42, v62, v43
	v_div_scale_f32 v57, s[8:9], v52, v40, v52
	v_fmac_f32_e32 v61, v65, v61
	v_mul_f32_e32 v64, v55, v60
	v_fma_f32 v67, -v48, v63, v49
	v_fmac_f32_e32 v62, v66, v58
	v_mul_f32_e32 v65, v57, v61
	v_fma_f32 v68, -v54, v64, v55
	v_fmac_f32_e32 v63, v67, v59
	v_fma_f32 v42, -v42, v62, v43
	v_fma_f32 v69, -v56, v65, v57
	v_fmac_f32_e32 v64, v68, v60
	v_fma_f32 v43, -v48, v63, v49
	v_div_fmas_f32 v42, v42, v58, v62
	s_mov_b64 vcc, s[4:5]
	v_fmac_f32_e32 v65, v69, v61
	v_fma_f32 v48, -v54, v64, v55
	v_div_fixup_f32 v15, v42, v15, v51
	v_div_fmas_f32 v42, v43, v59, v63
	s_mov_b64 vcc, s[6:7]
	v_fma_f32 v49, -v56, v65, v57
	v_div_fixup_f32 v14, v42, v14, v50
	v_div_fmas_f32 v42, v48, v60, v64
	s_mov_b64 vcc, s[8:9]
	v_pk_mul_f32 v[14:15], v[28:29], v[14:15]
	v_div_fmas_f32 v28, v49, v61, v65
	v_div_fixup_f32 v29, v42, v41, v53
	v_div_fixup_f32 v28, v28, v40, v52
	v_pk_mul_f32 v[28:29], v[30:31], v[28:29]
	v_cvt_pk_bf16_f32 v14, v14, v15
	v_cvt_pk_bf16_f32 v15, v28, v29
	global_store_dwordx2 v[4:5], v[14:15], off offset:128
	v_mov_b32_e32 v14, v118
	v_mov_b32_e32 v15, v119
	v_pk_mul_f32 v[28:29], v[38:39], v[12:13] op_sel_hi:[1,0]
	v_pk_mul_f32 v[30:31], v[36:37], v[12:13] op_sel_hi:[1,0]
	s_waitcnt vmcnt(1)
; __device__ __forceinline__ unsigned cvtpk(float lo, float hi) { f32x2 v = {lo, hi}; bf16x2_t b = __builtin_convertvector(v, bf16x2_t); return __builtin_bit_cast(unsigned, b); }
; __device__ __forceinline__ float bf2f(unsigned u16) { return __uint_as_float(u16 << 16); }
; __device__ __forceinline__ float silu(float g) { return g / (1.f + __expf(-g)); }
; template <int MODE>
; __device__ __forceinline__ void attn_unit(const UnitP& P, ALAS char* lds, const float* __restrict__ sub_gain, const int wv0, unsigned& hgen, unsigned* qctr, const int xcd) {
;     ...
;                 for (int d0 = 0; d0 < 4; ++d0)
; #pragma unroll
;                     for (int g = 0; g < 4; ++g) {
;                         const u32x2 gg = *(const u32x2*)(gp + 32 * d0 + 8 * g);
;                         const f32x4 sg = *(const f32x4*)(sub_gain + 32 * d0 + 8 * g + 4 * hi);
;                         const float y0 = o[d0][4 * g + 0] * rn * sg[0] * silu(bf2f(gg.x & 0xffffu)), y1 = o[d0][4 * g + 1] * rn * sg[1] * silu(bf2f(gg.x >> 16));
;                         const float y2 = o[d0][4 * g + 2] * rn * sg[2] * silu(bf2f(gg.y & 0xffffu)), y3 = o[d0][4 * g + 3] * rn * sg[3] * silu(bf2f(gg.y >> 16));
;                         u32x2 w; w.x = cvtpk(y0, y1); w.y = cvtpk(y2, y3);
;                         *(u32x2*)(mp + 32 * d0 + 8 * g) = w;
	v_pk_mul_f32 v[28:29], v[28:29], v[44:45]
	v_pk_mul_f32 v[30:31], v[30:31], v[46:47]
	v_lshlrev_b32_e32 v38, 16, v14
	v_and_b32_e32 v39, 0xffff0000, v14
	v_lshlrev_b32_e32 v40, 16, v15
	v_and_b32_e32 v41, 0xffff0000, v15
	v_mul_f32_e32 v14, 0xbfb8aa3b, v38
	v_mul_f32_e32 v15, 0xbfb8aa3b, v39
	v_exp_f32_e32 v14, v14
	v_exp_f32_e32 v15, v15
	v_mul_f32_e32 v36, 0xbfb8aa3b, v40
	v_mul_f32_e32 v37, 0xbfb8aa3b, v41
	v_exp_f32_e32 v36, v36
	v_exp_f32_e32 v37, v37
	v_pk_add_f32 v[14:15], v[14:15], 1.0 op_sel_hi:[1,0]
	v_pk_add_f32 v[36:37], v[36:37], 1.0 op_sel_hi:[1,0]
	v_div_scale_f32 v42, s[4:5], v15, v15, v39
	v_div_scale_f32 v44, s[4:5], v14, v14, v38
	v_rcp_f32_e32 v50, v42
	v_div_scale_f32 v46, s[6:7], v37, v37, v41
	v_rcp_f32_e32 v51, v44
	v_div_scale_f32 v48, s[8:9], v36, v36, v40
	v_rcp_f32_e32 v52, v46
	v_rcp_f32_e32 v53, v48
	v_fma_f32 v54, -v42, v50, 1.0
	v_div_scale_f32 v43, vcc, v39, v15, v39
	v_fma_f32 v55, -v44, v51, 1.0
	v_fmac_f32_e32 v50, v54, v50
	v_div_scale_f32 v45, s[4:5], v38, v14, v38
	v_fma_f32 v56, -v46, v52, 1.0
	v_fmac_f32_e32 v51, v55, v51
	v_mul_f32_e32 v54, v43, v50
	v_div_scale_f32 v47, s[6:7], v41, v37, v41
	v_fma_f32 v57, -v48, v53, 1.0
	v_fmac_f32_e32 v52, v56, v52
	v_mul_f32_e32 v55, v45, v51
	v_fma_f32 v58, -v42, v54, v43
	v_div_scale_f32 v49, s[8:9], v40, v36, v40
	v_fmac_f32_e32 v53, v57, v53
	v_mul_f32_e32 v56, v47, v52
	v_fma_f32 v59, -v44, v55, v45
	v_fmac_f32_e32 v54, v58, v50
	v_mul_f32_e32 v57, v49, v53
	v_fma_f32 v60, -v46, v56, v47
	v_fmac_f32_e32 v55, v59, v51
	v_fma_f32 v42, -v42, v54, v43
	v_fma_f32 v61, -v48, v57, v49
	v_fmac_f32_e32 v56, v60, v52
	v_fma_f32 v43, -v44, v55, v45
	v_div_fmas_f32 v42, v42, v50, v54
	s_mov_b64 vcc, s[4:5]
	v_fmac_f32_e32 v57, v61, v53
	v_fma_f32 v44, -v46, v56, v47
	v_div_fixup_f32 v15, v42, v15, v39
	v_div_fmas_f32 v39, v43, v51, v55
	s_mov_b64 vcc, s[6:7]
	v_fma_f32 v45, -v48, v57, v49
	v_div_fixup_f32 v14, v39, v14, v38
	v_div_fmas_f32 v38, v44, v52, v56
	s_mov_b64 vcc, s[8:9]
	v_pk_mul_f32 v[14:15], v[28:29], v[14:15]
	v_div_fmas_f32 v28, v45, v53, v57
	v_div_fixup_f32 v29, v38, v37, v41
	v_div_fixup_f32 v28, v28, v36, v40
	v_pk_mul_f32 v[28:29], v[30:31], v[28:29]
	v_cvt_pk_bf16_f32 v14, v14, v15
	v_cvt_pk_bf16_f32 v15, v28, v29
	global_store_dwordx2 v[4:5], v[14:15], off offset:144
	v_mov_b32_e32 v14, v120
	v_mov_b32_e32 v15, v121
	s_nop 0
	global_load_dwordx4 v[28:31], v13, s[12:13] offset:320
	global_load_dwordx4 v[36:39], v13, s[12:13] offset:352
	v_lshlrev_b32_e32 v42, 16, v14
	v_and_b32_e32 v43, 0xffff0000, v14
	v_lshlrev_b32_e32 v44, 16, v15
	v_and_b32_e32 v45, 0xffff0000, v15
	v_mul_f32_e32 v14, 0xbfb8aa3b, v42
	v_mul_f32_e32 v15, 0xbfb8aa3b, v43
	v_exp_f32_e32 v14, v14
	v_exp_f32_e32 v15, v15
	v_mul_f32_e32 v40, 0xbfb8aa3b, v44
	v_mul_f32_e32 v41, 0xbfb8aa3b, v45
	v_exp_f32_e32 v40, v40
	v_exp_f32_e32 v41, v41
	v_pk_add_f32 v[14:15], v[14:15], 1.0 op_sel_hi:[1,0]
	s_waitcnt vmcnt(1)
	v_pk_mul_f32 v[30:31], v[34:35], v[30:31]
	v_div_scale_f32 v34, s[4:5], v15, v15, v43
	v_pk_mul_f32 v[28:29], v[32:33], v[28:29]
	v_pk_add_f32 v[32:33], v[40:41], 1.0 op_sel_hi:[1,0]
	v_div_scale_f32 v40, s[4:5], v14, v14, v42
	v_rcp_f32_e32 v50, v34
	v_div_scale_f32 v46, s[6:7], v33, v33, v45
	v_rcp_f32_e32 v51, v40
	v_div_scale_f32 v48, s[8:9], v32, v32, v44
	v_rcp_f32_e32 v52, v46
	v_rcp_f32_e32 v53, v48
	v_fma_f32 v54, -v34, v50, 1.0
	v_div_scale_f32 v35, vcc, v43, v15, v43
	v_fma_f32 v55, -v40, v51, 1.0
	v_fmac_f32_e32 v50, v54, v50
	v_div_scale_f32 v41, s[4:5], v42, v14, v42
	v_fma_f32 v56, -v46, v52, 1.0
	v_fmac_f32_e32 v51, v55, v51
	v_mul_f32_e32 v54, v35, v50
	v_div_scale_f32 v47, s[6:7], v45, v33, v45
	v_fma_f32 v57, -v48, v53, 1.0
	v_fmac_f32_e32 v52, v56, v52
	v_mul_f32_e32 v55, v41, v51
	v_fma_f32 v58, -v34, v54, v35
	v_div_scale_f32 v49, s[8:9], v44, v32, v44
	v_fmac_f32_e32 v53, v57, v53
	v_mul_f32_e32 v56, v47, v52
	v_fma_f32 v59, -v40, v55, v41
	v_fmac_f32_e32 v54, v58, v50
	v_mul_f32_e32 v57, v49, v53
	v_fma_f32 v60, -v46, v56, v47
	v_fmac_f32_e32 v55, v59, v51
	v_fma_f32 v34, -v34, v54, v35
	v_fma_f32 v61, -v48, v57, v49
	v_fmac_f32_e32 v56, v60, v52
	v_fma_f32 v35, -v40, v55, v41
	v_div_fmas_f32 v34, v34, v50, v54
	s_mov_b64 vcc, s[4:5]
	v_fmac_f32_e32 v57, v61, v53
	v_fma_f32 v40, -v46, v56, v47
	v_div_fixup_f32 v15, v34, v15, v43
	v_div_fmas_f32 v34, v35, v51, v55
	s_mov_b64 vcc, s[6:7]
	v_fma_f32 v41, -v48, v57, v49
	v_div_fixup_f32 v14, v34, v14, v42
	v_div_fmas_f32 v34, v40, v52, v56
	s_mov_b64 vcc, s[8:9]
	v_pk_mul_f32 v[14:15], v[28:29], v[14:15]
	v_div_fmas_f32 v28, v41, v53, v57
	v_div_fixup_f32 v29, v34, v33, v45
	v_div_fixup_f32 v28, v28, v32, v44
	v_pk_mul_f32 v[28:29], v[30:31], v[28:29]
	v_cvt_pk_bf16_f32 v14, v14, v15
	v_cvt_pk_bf16_f32 v15, v28, v29
	global_store_dwordx2 v[4:5], v[14:15], off offset:160
	v_mov_b32_e32 v14, v122
	v_mov_b32_e32 v15, v123
	s_waitcnt vmcnt(1)
; __device__ __forceinline__ unsigned cvtpk(float lo, float hi) { f32x2 v = {lo, hi}; bf16x2_t b = __builtin_convertvector(v, bf16x2_t); return __builtin_bit_cast(unsigned, b); }
; __device__ __forceinline__ float bf2f(unsigned u16) { return __uint_as_float(u16 << 16); }
; __device__ __forceinline__ float silu(float g) { return g / (1.f + __expf(-g)); }
; template <int MODE>
; __device__ __forceinline__ void attn_unit(const UnitP& P, ALAS char* lds, const float* __restrict__ sub_gain, const int wv0, unsigned& hgen, unsigned* qctr, const int xcd) {
;     ...
;                 for (int d0 = 0; d0 < 4; ++d0)
; #pragma unroll
;                     for (int g = 0; g < 4; ++g) {
;                         const u32x2 gg = *(const u32x2*)(gp + 32 * d0 + 8 * g);
;                         const f32x4 sg = *(const f32x4*)(sub_gain + 32 * d0 + 8 * g + 4 * hi);
;                         const float y0 = o[d0][4 * g + 0] * rn * sg[0] * silu(bf2f(gg.x & 0xffffu)), y1 = o[d0][4 * g + 1] * rn * sg[1] * silu(bf2f(gg.x >> 16));
;                         const float y2 = o[d0][4 * g + 2] * rn * sg[2] * silu(bf2f(gg.y & 0xffffu)), y3 = o[d0][4 * g + 3] * rn * sg[3] * silu(bf2f(gg.y >> 16));
;                         u32x2 w; w.x = cvtpk(y0, y1); w.y = cvtpk(y2, y3);
;                         *(u32x2*)(mp + 32 * d0 + 8 * g) = w;
	v_pk_mul_f32 v[26:27], v[26:27], v[36:37]
	v_pk_mul_f32 v[24:25], v[24:25], v[38:39]
	v_lshlrev_b32_e32 v30, 16, v14
	v_and_b32_e32 v31, 0xffff0000, v14
	v_lshlrev_b32_e32 v32, 16, v15
	v_and_b32_e32 v33, 0xffff0000, v15
	v_mul_f32_e32 v14, 0xbfb8aa3b, v30
	v_mul_f32_e32 v15, 0xbfb8aa3b, v31
	v_exp_f32_e32 v14, v14
	v_exp_f32_e32 v15, v15
	v_mul_f32_e32 v28, 0xbfb8aa3b, v32
	v_mul_f32_e32 v29, 0xbfb8aa3b, v33
	v_exp_f32_e32 v28, v28
	v_exp_f32_e32 v29, v29
	v_pk_add_f32 v[14:15], v[14:15], 1.0 op_sel_hi:[1,0]
	v_pk_add_f32 v[28:29], v[28:29], 1.0 op_sel_hi:[1,0]
	v_div_scale_f32 v34, s[4:5], v15, v15, v31
	v_div_scale_f32 v36, s[4:5], v14, v14, v30
	v_rcp_f32_e32 v42, v34
	v_div_scale_f32 v38, s[6:7], v29, v29, v33
	v_rcp_f32_e32 v43, v36
	v_div_scale_f32 v40, s[8:9], v28, v28, v32
	v_rcp_f32_e32 v44, v38
	v_rcp_f32_e32 v45, v40
	v_fma_f32 v46, -v34, v42, 1.0
	v_div_scale_f32 v35, vcc, v31, v15, v31
	v_fma_f32 v47, -v36, v43, 1.0
	v_fmac_f32_e32 v42, v46, v42
	v_div_scale_f32 v37, s[4:5], v30, v14, v30
	v_fma_f32 v48, -v38, v44, 1.0
	v_fmac_f32_e32 v43, v47, v43
	v_mul_f32_e32 v46, v35, v42
	v_div_scale_f32 v39, s[6:7], v33, v29, v33
	v_fma_f32 v49, -v40, v45, 1.0
	v_fmac_f32_e32 v44, v48, v44
	v_mul_f32_e32 v47, v37, v43
	v_fma_f32 v50, -v34, v46, v35
	v_div_scale_f32 v41, s[8:9], v32, v28, v32
	v_fmac_f32_e32 v45, v49, v45
	v_mul_f32_e32 v48, v39, v44
	v_fma_f32 v51, -v36, v47, v37
	v_fmac_f32_e32 v46, v50, v42
	v_mul_f32_e32 v49, v41, v45
	v_fma_f32 v52, -v38, v48, v39
	v_fmac_f32_e32 v47, v51, v43
	v_fma_f32 v34, -v34, v46, v35
	v_fma_f32 v53, -v40, v49, v41
	v_fmac_f32_e32 v48, v52, v44
	v_fma_f32 v35, -v36, v47, v37
	v_div_fmas_f32 v34, v34, v42, v46
	s_mov_b64 vcc, s[4:5]
	v_fmac_f32_e32 v49, v53, v45
	v_fma_f32 v36, -v38, v48, v39
	v_div_fixup_f32 v15, v34, v15, v31
	v_div_fmas_f32 v31, v35, v43, v47
	s_mov_b64 vcc, s[6:7]
	v_fma_f32 v37, -v40, v49, v41
	v_div_fixup_f32 v14, v31, v14, v30
	v_div_fmas_f32 v30, v36, v44, v48
	s_mov_b64 vcc, s[8:9]
	v_pk_mul_f32 v[14:15], v[26:27], v[14:15]
	v_div_fmas_f32 v26, v37, v45, v49
	v_div_fixup_f32 v27, v30, v29, v33
	v_div_fixup_f32 v26, v26, v28, v32
	v_pk_mul_f32 v[24:25], v[24:25], v[26:27]
	v_cvt_pk_bf16_f32 v14, v14, v15
	v_cvt_pk_bf16_f32 v15, v24, v25
	global_store_dwordx2 v[4:5], v[14:15], off offset:176
	v_mov_b32_e32 v14, v124
	v_mov_b32_e32 v15, v125
	s_nop 0
	global_load_dwordx4 v[24:27], v13, s[12:13] offset:384
	global_load_dwordx4 v[28:31], v13, s[12:13] offset:416
	v_lshlrev_b32_e32 v34, 16, v14
	v_and_b32_e32 v35, 0xffff0000, v14
	v_lshlrev_b32_e32 v36, 16, v15
	v_and_b32_e32 v37, 0xffff0000, v15
	v_mul_f32_e32 v14, 0xbfb8aa3b, v34
	v_mul_f32_e32 v15, 0xbfb8aa3b, v35
	v_exp_f32_e32 v14, v14
	v_exp_f32_e32 v15, v15
	v_mul_f32_e32 v32, 0xbfb8aa3b, v36
	v_mul_f32_e32 v33, 0xbfb8aa3b, v37
	v_exp_f32_e32 v32, v32
	v_exp_f32_e32 v33, v33
	v_pk_add_f32 v[14:15], v[14:15], 1.0 op_sel_hi:[1,0]
	s_waitcnt vmcnt(1)
	v_pk_mul_f32 v[22:23], v[22:23], v[26:27]
	v_div_scale_f32 v26, s[4:5], v15, v15, v35
	v_pk_mul_f32 v[20:21], v[20:21], v[24:25]
	v_pk_add_f32 v[24:25], v[32:33], 1.0 op_sel_hi:[1,0]
	v_div_scale_f32 v32, s[4:5], v14, v14, v34
	v_rcp_f32_e32 v42, v26
	v_div_scale_f32 v38, s[6:7], v25, v25, v37
	v_rcp_f32_e32 v43, v32
	v_div_scale_f32 v40, s[8:9], v24, v24, v36
	v_rcp_f32_e32 v44, v38
	v_rcp_f32_e32 v45, v40
	v_fma_f32 v46, -v26, v42, 1.0
	v_div_scale_f32 v27, vcc, v35, v15, v35
	v_fma_f32 v47, -v32, v43, 1.0
	v_fmac_f32_e32 v42, v46, v42
	v_div_scale_f32 v33, s[4:5], v34, v14, v34
	v_fma_f32 v48, -v38, v44, 1.0
	v_fmac_f32_e32 v43, v47, v43
	v_mul_f32_e32 v46, v27, v42
	v_div_scale_f32 v39, s[6:7], v37, v25, v37
	v_fma_f32 v49, -v40, v45, 1.0
	v_fmac_f32_e32 v44, v48, v44
	v_mul_f32_e32 v47, v33, v43
	v_fma_f32 v50, -v26, v46, v27
	v_div_scale_f32 v41, s[8:9], v36, v24, v36
	v_fmac_f32_e32 v45, v49, v45
	v_mul_f32_e32 v48, v39, v44
	v_fma_f32 v51, -v32, v47, v33
	v_fmac_f32_e32 v46, v50, v42
	v_mul_f32_e32 v49, v41, v45
	v_fma_f32 v52, -v38, v48, v39
	v_fmac_f32_e32 v47, v51, v43
	v_fma_f32 v26, -v26, v46, v27
	v_fma_f32 v53, -v40, v49, v41
	v_fmac_f32_e32 v48, v52, v44
	v_fma_f32 v27, -v32, v47, v33
	v_div_fmas_f32 v26, v26, v42, v46
	s_mov_b64 vcc, s[4:5]
	v_fmac_f32_e32 v49, v53, v45
	v_fma_f32 v32, -v38, v48, v39
	v_div_fixup_f32 v15, v26, v15, v35
	v_div_fmas_f32 v26, v27, v43, v47
	s_mov_b64 vcc, s[6:7]
	v_fma_f32 v33, -v40, v49, v41
	v_div_fixup_f32 v14, v26, v14, v34
	v_div_fmas_f32 v26, v32, v44, v48
	s_mov_b64 vcc, s[8:9]
	v_pk_mul_f32 v[14:15], v[20:21], v[14:15]
	v_div_fmas_f32 v20, v33, v45, v49
	v_div_fixup_f32 v21, v26, v25, v37
	v_div_fixup_f32 v20, v20, v24, v36
	v_pk_mul_f32 v[20:21], v[22:23], v[20:21]
	v_cvt_pk_bf16_f32 v14, v14, v15
	v_cvt_pk_bf16_f32 v15, v20, v21
	global_store_dwordx2 v[4:5], v[14:15], off offset:192
	v_mov_b32_e32 v14, v126
	v_mov_b32_e32 v15, v127
	s_waitcnt vmcnt(1)
; __device__ __forceinline__ unsigned cvtpk(float lo, float hi) { f32x2 v = {lo, hi}; bf16x2_t b = __builtin_convertvector(v, bf16x2_t); return __builtin_bit_cast(unsigned, b); }
; __device__ __forceinline__ float bf2f(unsigned u16) { return __uint_as_float(u16 << 16); }
; __device__ __forceinline__ float silu(float g) { return g / (1.f + __expf(-g)); }
; template <int MODE>
; __device__ __forceinline__ void attn_unit(const UnitP& P, ALAS char* lds, const float* __restrict__ sub_gain, const int wv0, unsigned& hgen, unsigned* qctr, const int xcd) {
;     ...
;                 for (int d0 = 0; d0 < 4; ++d0)
; #pragma unroll
;                     for (int g = 0; g < 4; ++g) {
;                         const u32x2 gg = *(const u32x2*)(gp + 32 * d0 + 8 * g);
;                         const f32x4 sg = *(const f32x4*)(sub_gain + 32 * d0 + 8 * g + 4 * hi);
;                         const float y0 = o[d0][4 * g + 0] * rn * sg[0] * silu(bf2f(gg.x & 0xffffu)), y1 = o[d0][4 * g + 1] * rn * sg[1] * silu(bf2f(gg.x >> 16));
;                         const float y2 = o[d0][4 * g + 2] * rn * sg[2] * silu(bf2f(gg.y & 0xffffu)), y3 = o[d0][4 * g + 3] * rn * sg[3] * silu(bf2f(gg.y >> 16));
;                         u32x2 w; w.x = cvtpk(y0, y1); w.y = cvtpk(y2, y3);
;                         *(u32x2*)(mp + 32 * d0 + 8 * g) = w;
	v_pk_mul_f32 v[18:19], v[18:19], v[28:29]
	v_pk_mul_f32 v[16:17], v[16:17], v[30:31]
	v_lshlrev_b32_e32 v22, 16, v14
	v_and_b32_e32 v23, 0xffff0000, v14
	v_lshlrev_b32_e32 v24, 16, v15
	v_and_b32_e32 v25, 0xffff0000, v15
	v_mul_f32_e32 v14, 0xbfb8aa3b, v22
	v_mul_f32_e32 v15, 0xbfb8aa3b, v23
	v_exp_f32_e32 v14, v14
	v_exp_f32_e32 v15, v15
	v_mul_f32_e32 v20, 0xbfb8aa3b, v24
	v_mul_f32_e32 v21, 0xbfb8aa3b, v25
	v_exp_f32_e32 v20, v20
	v_exp_f32_e32 v21, v21
	v_pk_add_f32 v[14:15], v[14:15], 1.0 op_sel_hi:[1,0]
	v_pk_add_f32 v[20:21], v[20:21], 1.0 op_sel_hi:[1,0]
	v_div_scale_f32 v26, s[4:5], v15, v15, v23
	v_div_scale_f32 v28, s[4:5], v14, v14, v22
	v_rcp_f32_e32 v34, v26
	v_div_scale_f32 v30, s[6:7], v21, v21, v25
	v_rcp_f32_e32 v35, v28
	v_div_scale_f32 v32, s[8:9], v20, v20, v24
	v_rcp_f32_e32 v36, v30
	v_rcp_f32_e32 v37, v32
	v_fma_f32 v38, -v26, v34, 1.0
	v_div_scale_f32 v27, vcc, v23, v15, v23
	v_fma_f32 v39, -v28, v35, 1.0
	v_fmac_f32_e32 v34, v38, v34
	v_div_scale_f32 v29, s[4:5], v22, v14, v22
	v_fma_f32 v40, -v30, v36, 1.0
	v_fmac_f32_e32 v35, v39, v35
	v_mul_f32_e32 v38, v27, v34
	v_div_scale_f32 v31, s[6:7], v25, v21, v25
	v_fma_f32 v41, -v32, v37, 1.0
	v_fmac_f32_e32 v36, v40, v36
	v_mul_f32_e32 v39, v29, v35
	v_fma_f32 v42, -v26, v38, v27
	v_div_scale_f32 v33, s[8:9], v24, v20, v24
	v_fmac_f32_e32 v37, v41, v37
	v_mul_f32_e32 v40, v31, v36
	v_fma_f32 v43, -v28, v39, v29
	v_fmac_f32_e32 v38, v42, v34
	v_mul_f32_e32 v41, v33, v37
	v_fma_f32 v44, -v30, v40, v31
	v_fmac_f32_e32 v39, v43, v35
	v_fma_f32 v26, -v26, v38, v27
	v_fma_f32 v45, -v32, v41, v33
	v_fmac_f32_e32 v40, v44, v36
	v_fma_f32 v27, -v28, v39, v29
	v_div_fmas_f32 v26, v26, v34, v38
	s_mov_b64 vcc, s[4:5]
	v_fmac_f32_e32 v41, v45, v37
	v_fma_f32 v28, -v30, v40, v31
	v_div_fixup_f32 v15, v26, v15, v23
	v_div_fmas_f32 v23, v27, v35, v39
	s_mov_b64 vcc, s[6:7]
	v_fma_f32 v29, -v32, v41, v33
	v_div_fixup_f32 v14, v23, v14, v22
	v_div_fmas_f32 v22, v28, v36, v40
	s_mov_b64 vcc, s[8:9]
	v_pk_mul_f32 v[14:15], v[18:19], v[14:15]
	v_div_fmas_f32 v18, v29, v37, v41
	v_div_fixup_f32 v19, v22, v21, v25
	v_div_fixup_f32 v18, v18, v20, v24
	v_pk_mul_f32 v[16:17], v[16:17], v[18:19]
	v_cvt_pk_bf16_f32 v14, v14, v15
	v_cvt_pk_bf16_f32 v15, v16, v17
	global_store_dwordx2 v[4:5], v[14:15], off offset:208
	v_mov_b32_e32 v22, v128
	v_mov_b32_e32 v23, v129
	s_nop 0
	global_load_dwordx4 v[14:17], v13, s[12:13] offset:448
	global_load_dwordx4 v[18:21], v13, s[12:13] offset:480
	v_lshlrev_b32_e32 v13, 16, v22
	v_and_b32_e32 v26, 0xffff0000, v22
	v_lshlrev_b32_e32 v27, 16, v23
	v_and_b32_e32 v28, 0xffff0000, v23
	v_mul_f32_e32 v22, 0xbfb8aa3b, v13
	v_mul_f32_e32 v23, 0xbfb8aa3b, v26
	v_exp_f32_e32 v22, v22
	v_exp_f32_e32 v23, v23
	v_mul_f32_e32 v24, 0xbfb8aa3b, v27
	v_mul_f32_e32 v25, 0xbfb8aa3b, v28
	v_exp_f32_e32 v24, v24
	v_exp_f32_e32 v25, v25
	s_waitcnt vmcnt(1)
; __device__ __forceinline__ unsigned cvtpk(float lo, float hi) { f32x2 v = {lo, hi}; bf16x2_t b = __builtin_convertvector(v, bf16x2_t); return __builtin_bit_cast(unsigned, b); }
; __device__ __forceinline__ float bf2f(unsigned u16) { return __uint_as_float(u16 << 16); }
; __device__ __forceinline__ float silu(float g) { return g / (1.f + __expf(-g)); }
; template <int MODE>
; __device__ __forceinline__ void attn_unit(const UnitP& P, ALAS char* lds, const float* __restrict__ sub_gain, const int wv0, unsigned& hgen, unsigned* qctr, const int xcd) {
;     ...
;                 for (int d0 = 0; d0 < 4; ++d0)
; #pragma unroll
;                     for (int g = 0; g < 4; ++g) {
;                         const u32x2 gg = *(const u32x2*)(gp + 32 * d0 + 8 * g);
;                         const f32x4 sg = *(const f32x4*)(sub_gain + 32 * d0 + 8 * g + 4 * hi);
;                         const float y0 = o[d0][4 * g + 0] * rn * sg[0] * silu(bf2f(gg.x & 0xffffu)), y1 = o[d0][4 * g + 1] * rn * sg[1] * silu(bf2f(gg.x >> 16));
;                         const float y2 = o[d0][4 * g + 2] * rn * sg[2] * silu(bf2f(gg.y & 0xffffu)), y3 = o[d0][4 * g + 3] * rn * sg[3] * silu(bf2f(gg.y >> 16));
;                         u32x2 w; w.x = cvtpk(y0, y1); w.y = cvtpk(y2, y3);
;                         *(u32x2*)(mp + 32 * d0 + 8 * g) = w;
	v_pk_mul_f32 v[8:9], v[8:9], v[14:15]
	v_pk_add_f32 v[14:15], v[22:23], 1.0 op_sel_hi:[1,0]
	v_pk_mul_f32 v[10:11], v[10:11], v[16:17]
	v_div_scale_f32 v22, s[4:5], v15, v15, v26
	v_pk_add_f32 v[16:17], v[24:25], 1.0 op_sel_hi:[1,0]
	v_div_scale_f32 v24, s[4:5], v14, v14, v13
	v_rcp_f32_e32 v33, v22
	v_div_scale_f32 v29, s[6:7], v17, v17, v28
	v_rcp_f32_e32 v34, v24
	v_div_scale_f32 v31, s[8:9], v16, v16, v27
	v_rcp_f32_e32 v35, v29
	v_rcp_f32_e32 v36, v31
	v_fma_f32 v37, -v22, v33, 1.0
	v_div_scale_f32 v23, vcc, v26, v15, v26
	v_fma_f32 v38, -v24, v34, 1.0
	v_fmac_f32_e32 v33, v37, v33
	v_div_scale_f32 v25, s[4:5], v13, v14, v13
	v_fma_f32 v39, -v29, v35, 1.0
	v_fmac_f32_e32 v34, v38, v34
	v_mul_f32_e32 v37, v23, v33
	v_div_scale_f32 v30, s[6:7], v28, v17, v28
	v_fma_f32 v40, -v31, v36, 1.0
	v_fmac_f32_e32 v35, v39, v35
	v_mul_f32_e32 v38, v25, v34
	v_fma_f32 v41, -v22, v37, v23
	v_div_scale_f32 v32, s[8:9], v27, v16, v27
	v_fmac_f32_e32 v36, v40, v36
	v_mul_f32_e32 v39, v30, v35
	v_fma_f32 v42, -v24, v38, v25
	v_fmac_f32_e32 v37, v41, v33
	v_mul_f32_e32 v40, v32, v36
	v_fma_f32 v43, -v29, v39, v30
	v_fmac_f32_e32 v38, v42, v34
	v_fma_f32 v22, -v22, v37, v23
	v_fma_f32 v44, -v31, v40, v32
	v_fmac_f32_e32 v39, v43, v35
	v_fma_f32 v23, -v24, v38, v25
	v_div_fmas_f32 v22, v22, v33, v37
	s_mov_b64 vcc, s[4:5]
	v_fmac_f32_e32 v40, v44, v36
	v_fma_f32 v24, -v29, v39, v30
	v_div_fixup_f32 v15, v22, v15, v26
	v_div_fmas_f32 v22, v23, v34, v38
	s_mov_b64 vcc, s[6:7]
	v_fma_f32 v25, -v31, v40, v32
	v_div_fixup_f32 v14, v22, v14, v13
	v_div_fmas_f32 v13, v24, v35, v39
	s_mov_b64 vcc, s[8:9]
	v_pk_mul_f32 v[8:9], v[8:9], v[14:15]
	v_div_fixup_f32 v15, v13, v17, v28
	v_div_fmas_f32 v13, v25, v36, v40
	v_div_fixup_f32 v14, v13, v16, v27
	v_pk_mul_f32 v[10:11], v[10:11], v[14:15]
	v_cvt_pk_bf16_f32 v8, v8, v9
	v_cvt_pk_bf16_f32 v9, v10, v11
	global_store_dwordx2 v[4:5], v[8:9], off offset:224
	v_mov_b32_e32 v6, v130
	v_mov_b32_e32 v7, v131
	v_pk_mul_f32 v[2:3], v[2:3], v[12:13] op_sel_hi:[1,0]
	v_pk_mul_f32 v[0:1], v[0:1], v[12:13] op_sel_hi:[1,0]
	s_waitcnt vmcnt(1)
	v_pk_mul_f32 v[2:3], v[2:3], v[18:19]
	v_pk_mul_f32 v[0:1], v[0:1], v[20:21]
	v_lshlrev_b32_e32 v10, 16, v6
	v_and_b32_e32 v11, 0xffff0000, v6
	v_lshlrev_b32_e32 v12, 16, v7
	v_and_b32_e32 v13, 0xffff0000, v7
	v_mul_f32_e32 v6, 0xbfb8aa3b, v10
	v_mul_f32_e32 v7, 0xbfb8aa3b, v11
	v_exp_f32_e32 v6, v6
	v_exp_f32_e32 v7, v7
	v_mul_f32_e32 v8, 0xbfb8aa3b, v12
	v_mul_f32_e32 v9, 0xbfb8aa3b, v13
	v_exp_f32_e32 v8, v8
	v_exp_f32_e32 v9, v9
	v_pk_add_f32 v[6:7], v[6:7], 1.0 op_sel_hi:[1,0]
	v_pk_add_f32 v[8:9], v[8:9], 1.0 op_sel_hi:[1,0]
	v_div_scale_f32 v14, s[4:5], v7, v7, v11
	v_div_scale_f32 v16, s[4:5], v6, v6, v10
	v_rcp_f32_e32 v22, v14
	v_div_scale_f32 v18, s[6:7], v9, v9, v13
	v_rcp_f32_e32 v23, v16
	v_div_scale_f32 v20, s[8:9], v8, v8, v12
	v_rcp_f32_e32 v24, v18
	v_rcp_f32_e32 v25, v20
	v_fma_f32 v26, -v14, v22, 1.0
	v_div_scale_f32 v15, vcc, v11, v7, v11
	v_fma_f32 v27, -v16, v23, 1.0
	v_fmac_f32_e32 v22, v26, v22
	v_div_scale_f32 v17, s[4:5], v10, v6, v10
	v_fma_f32 v28, -v18, v24, 1.0
	v_fmac_f32_e32 v23, v27, v23
	v_mul_f32_e32 v26, v15, v22
	v_div_scale_f32 v19, s[6:7], v13, v9, v13
	v_fma_f32 v29, -v20, v25, 1.0
	v_fmac_f32_e32 v24, v28, v24
	v_mul_f32_e32 v27, v17, v23
	v_fma_f32 v30, -v14, v26, v15
	v_div_scale_f32 v21, s[8:9], v12, v8, v12
	v_fmac_f32_e32 v25, v29, v25
	v_mul_f32_e32 v28, v19, v24
	v_fma_f32 v31, -v16, v27, v17
	v_fmac_f32_e32 v26, v30, v22
	v_mul_f32_e32 v29, v21, v25
	v_fma_f32 v32, -v18, v28, v19
	v_fmac_f32_e32 v27, v31, v23
	v_fma_f32 v14, -v14, v26, v15
	v_fma_f32 v33, -v20, v29, v21
	v_fmac_f32_e32 v28, v32, v24
	v_fma_f32 v15, -v16, v27, v17
	v_div_fmas_f32 v14, v14, v22, v26
	s_mov_b64 vcc, s[4:5]
	v_fmac_f32_e32 v29, v33, v25
	v_fma_f32 v16, -v18, v28, v19
	v_div_fixup_f32 v7, v14, v7, v11
	v_div_fmas_f32 v11, v15, v23, v27
	s_mov_b64 vcc, s[6:7]
	v_fma_f32 v17, -v20, v29, v21
	v_div_fixup_f32 v6, v11, v6, v10
	v_div_fmas_f32 v10, v16, v24, v28
	s_mov_b64 vcc, s[8:9]
	v_pk_mul_f32 v[2:3], v[2:3], v[6:7]
	v_div_fmas_f32 v6, v17, v25, v29
	v_div_fixup_f32 v7, v10, v9, v13
	v_div_fixup_f32 v6, v6, v8, v12
	v_pk_mul_f32 v[0:1], v[0:1], v[6:7]
	v_cvt_pk_bf16_f32 v2, v2, v3
	v_cvt_pk_bf16_f32 v3, v0, v1
	global_store_dwordx2 v[4:5], v[2:3], off offset:240

; __device__ __forceinline__ float sum32(float v) { auto rr = __builtin_amdgcn_permlane32_swap(__float_as_uint(v), __float_as_uint(v), false, false); return __uint_as_float(rr[0]) + __uint_as_float(rr[1]); }
; __device__ __forceinline__ unsigned cvtpk(float lo, float hi) { f32x2 v = {lo, hi}; bf16x2_t b = __builtin_convertvector(v, bf16x2_t); return __builtin_bit_cast(unsigned, b); }
; __device__ __forceinline__ float bf2f(unsigned u16) { return __uint_as_float(u16 << 16); }
; __device__ __forceinline__ float silu(float g) { return g / (1.f + __expf(-g)); }
; template <int MODE>
; __device__ __forceinline__ void attn_unit(const UnitP& P, ALAS char* lds, const float* __restrict__ sub_gain, const int wv0, unsigned& hgen, unsigned* qctr, const int xcd) {
;     ...
;     lsum = sum32(lsum);
;     const int qrow = qw0 + r32;
;     if constexpr (MODE == 1) {
;         if (active && qrow < P.nq && P.dry == 0) {
;             const float inv = 1.f / lsum;
;             const bf16_t* gp = P.G + (size_t)qrow * 8192 + 4 * hi;
;             bf16_t* mp = P.Mo + (size_t)qrow * 2048 + 4 * hi;
; #pragma unroll
;             for (int d0 = 0; d0 < 4; ++d0)
; #pragma unroll
;                 for (int g = 0; g < 4; ++g) {
;                     const u32x2 gg = *(const u32x2*)(gp + 32 * d0 + 8 * g);
;                     const float y0 = o[d0][4 * g + 0] * inv * silu(bf2f(gg.x & 0xffffu)), y1 = o[d0][4 * g + 1] * inv * silu(bf2f(gg.x >> 16));
;                     const float y2 = o[d0][4 * g + 2] * inv * silu(bf2f(gg.y & 0xffffu)), y3 = o[d0][4 * g + 3] * inv * silu(bf2f(gg.y >> 16));
;                     u32x2 w; w.x = cvtpk(y0, y1); w.y = cvtpk(y2, y3);
;                     *(u32x2*)(mp + 32 * d0 + 8 * g) = w;
.LBB0_417:
	v_readlane_b32 s0, v252, 44
	v_mov_b32_e32 v64, v204
	s_nop 1
	v_permlane32_swap_b32_e32 v204, v64
	v_cmp_gt_u32_e32 vcc, s0, v200
	s_and_b64 s[4:5], s[74:75], vcc
	s_and_saveexec_b64 s[0:1], s[4:5]
	s_cbranch_execz .LBB0_218
	v_readlane_b32 s4, v252, 40
	v_mov_b32_e32 v179, v177
	v_readlane_b32 s5, v252, 41
	v_lshlrev_b32_e32 v176, 1, v181
	v_mov_b32_e32 v65, v177
	v_lshl_add_u64 v[66:67], s[4:5], 0, v[178:179]
	v_lshl_add_u64 v[68:69], v[66:67], 0, v[176:177]
	global_load_dwordx2 v[70:71], v[68:69], off
	global_load_dwordx2 v[98:99], v[68:69], off offset:16
	global_load_dwordx2 v[100:101], v[68:69], off offset:32
	global_load_dwordx2 v[102:103], v[68:69], off offset:48
	global_load_dwordx2 v[104:105], v[68:69], off offset:64
	global_load_dwordx2 v[106:107], v[68:69], off offset:80
	global_load_dwordx2 v[108:109], v[68:69], off offset:96
	global_load_dwordx2 v[110:111], v[68:69], off offset:112
	global_load_dwordx2 v[112:113], v[68:69], off offset:128
	global_load_dwordx2 v[114:115], v[68:69], off offset:144
	global_load_dwordx2 v[116:117], v[68:69], off offset:160
	global_load_dwordx2 v[118:119], v[68:69], off offset:176
	global_load_dwordx2 v[120:121], v[68:69], off offset:192
	global_load_dwordx2 v[122:123], v[68:69], off offset:208
	global_load_dwordx2 v[124:125], v[68:69], off offset:224
	global_load_dwordx2 v[126:127], v[68:69], off offset:240
	v_add_f32_e32 v66, v204, v64
	v_div_scale_f32 v67, s[4:5], v66, v66, 1.0
	v_rcp_f32_e32 v72, v67
	v_div_scale_f32 v73, vcc, 1.0, v66, 1.0
	v_readlane_b32 s4, v252, 42
	v_fma_f32 v74, -v67, v72, 1.0
	v_fmac_f32_e32 v72, v74, v72
	v_mul_f32_e32 v74, v73, v72
	v_fma_f32 v75, -v67, v74, v73
	v_fmac_f32_e32 v74, v75, v72
	v_fma_f32 v67, -v67, v74, v73
	v_div_fmas_f32 v67, v67, v72, v74
	v_div_fixup_f32 v66, v67, v66, 1.0
	v_lshlrev_b32_e32 v64, 12, v200
	v_readlane_b32 s5, v252, 43
	s_waitcnt vmcnt(0)
	v_lshlrev_b32_e32 v67, 16, v70
	v_and_b32_e32 v74, 0xffff0000, v70
	v_lshlrev_b32_e32 v75, 16, v71
	v_and_b32_e32 v76, 0xffff0000, v71
	v_mul_f32_e32 v70, 0xbfb8aa3b, v67
	v_mul_f32_e32 v71, 0xbfb8aa3b, v74
	v_exp_f32_e32 v70, v70
	v_exp_f32_e32 v71, v71
	v_mul_f32_e32 v72, 0xbfb8aa3b, v75
	v_mul_f32_e32 v73, 0xbfb8aa3b, v76
	v_exp_f32_e32 v72, v72
	v_exp_f32_e32 v73, v73
	v_pk_add_f32 v[70:71], v[70:71], 1.0 op_sel_hi:[1,0]
	v_lshl_add_u64 v[64:65], s[4:5], 0, v[64:65]
	v_div_scale_f32 v77, s[4:5], v71, v71, v74
	v_pk_add_f32 v[72:73], v[72:73], 1.0 op_sel_hi:[1,0]
	v_div_scale_f32 v79, s[4:5], v70, v70, v67
	v_rcp_f32_e32 v85, v77
	v_div_scale_f32 v81, s[6:7], v73, v73, v76
	v_rcp_f32_e32 v86, v79
	v_div_scale_f32 v83, s[8:9], v72, v72, v75
	v_rcp_f32_e32 v87, v81
	v_rcp_f32_e32 v88, v83
	v_fma_f32 v89, -v77, v85, 1.0
	v_div_scale_f32 v78, vcc, v74, v71, v74
	v_fma_f32 v90, -v79, v86, 1.0
	v_fmac_f32_e32 v85, v89, v85
	v_div_scale_f32 v80, s[4:5], v67, v70, v67
	v_fma_f32 v91, -v81, v87, 1.0
	v_fmac_f32_e32 v86, v90, v86
	v_mul_f32_e32 v89, v78, v85
	v_div_scale_f32 v82, s[6:7], v76, v73, v76
	v_fma_f32 v92, -v83, v88, 1.0
	v_fmac_f32_e32 v87, v91, v87
	v_mul_f32_e32 v90, v80, v86
	v_fma_f32 v93, -v77, v89, v78
	v_div_scale_f32 v84, s[8:9], v75, v72, v75
	v_fmac_f32_e32 v88, v92, v88
	v_mul_f32_e32 v91, v82, v87
	v_fma_f32 v94, -v79, v90, v80
	v_fmac_f32_e32 v89, v93, v85
	v_mul_f32_e32 v92, v84, v88
	v_fma_f32 v95, -v81, v91, v82
	v_fmac_f32_e32 v90, v94, v86
	v_fma_f32 v77, -v77, v89, v78
	v_fma_f32 v96, -v83, v92, v84
	v_fmac_f32_e32 v91, v95, v87
	v_fma_f32 v78, -v79, v90, v80
	v_div_fmas_f32 v77, v77, v85, v89
	s_mov_b64 vcc, s[4:5]
	v_fmac_f32_e32 v92, v96, v88
	v_fma_f32 v79, -v81, v91, v82
	v_div_fixup_f32 v71, v77, v71, v74
	v_div_fmas_f32 v74, v78, v86, v90
	s_mov_b64 vcc, s[6:7]
	v_pk_mul_f32 v[48:49], v[48:49], v[66:67] op_sel_hi:[1,0]
	v_pk_mul_f32 v[50:51], v[50:51], v[66:67] op_sel_hi:[1,0]
	v_fma_f32 v80, -v83, v92, v84
	v_div_fixup_f32 v70, v74, v70, v67
	v_div_fmas_f32 v67, v79, v87, v91
	s_mov_b64 vcc, s[8:9]
	v_pk_mul_f32 v[48:49], v[48:49], v[70:71]
	v_div_fixup_f32 v71, v67, v73, v76
	v_div_fmas_f32 v67, v80, v88, v92
	v_div_fixup_f32 v70, v67, v72, v75
	v_pk_mul_f32 v[50:51], v[50:51], v[70:71]
	v_lshl_add_u64 v[64:65], v[64:65], 0, v[176:177]
	v_cvt_pk_bf16_f32 v48, v48, v49
	v_cvt_pk_bf16_f32 v49, v50, v51
	global_store_dwordx2 v[64:65], v[48:49], off
	v_mov_b32_e32 v48, v98
	v_mov_b32_e32 v49, v99
	v_lshlrev_b32_e32 v67, 16, v48
	v_and_b32_e32 v70, 0xffff0000, v48
	v_lshlrev_b32_e32 v71, 16, v49
	v_and_b32_e32 v72, 0xffff0000, v49
	v_mul_f32_e32 v48, 0xbfb8aa3b, v67
	v_mul_f32_e32 v49, 0xbfb8aa3b, v70
	v_exp_f32_e32 v48, v48
	v_exp_f32_e32 v49, v49
	v_mul_f32_e32 v50, 0xbfb8aa3b, v71
	v_mul_f32_e32 v51, 0xbfb8aa3b, v72
	v_exp_f32_e32 v50, v50
	v_exp_f32_e32 v51, v51
	v_pk_add_f32 v[48:49], v[48:49], 1.0 op_sel_hi:[1,0]
	v_pk_mul_f32 v[52:53], v[52:53], v[66:67] op_sel_hi:[1,0]
	v_div_scale_f32 v73, s[4:5], v49, v49, v70
	v_pk_add_f32 v[50:51], v[50:51], 1.0 op_sel_hi:[1,0]
	v_div_scale_f32 v75, s[4:5], v48, v48, v67
	v_rcp_f32_e32 v81, v73
	v_div_scale_f32 v77, s[6:7], v51, v51, v72
	v_rcp_f32_e32 v82, v75
	v_div_scale_f32 v79, s[8:9], v50, v50, v71
	v_rcp_f32_e32 v83, v77
	v_rcp_f32_e32 v84, v79
	v_fma_f32 v85, -v73, v81, 1.0
	v_div_scale_f32 v74, vcc, v70, v49, v70
	v_fma_f32 v86, -v75, v82, 1.0
	v_fmac_f32_e32 v81, v85, v81
	v_div_scale_f32 v76, s[4:5], v67, v48, v67
	v_fma_f32 v87, -v77, v83, 1.0
	v_fmac_f32_e32 v82, v86, v82
	v_mul_f32_e32 v85, v74, v81
	v_div_scale_f32 v78, s[6:7], v72, v51, v72
	v_fma_f32 v88, -v79, v84, 1.0
	v_fmac_f32_e32 v83, v87, v83
	v_mul_f32_e32 v86, v76, v82
	v_fma_f32 v89, -v73, v85, v74
	v_div_scale_f32 v80, s[8:9], v71, v50, v71
; __device__ __forceinline__ unsigned cvtpk(float lo, float hi) { f32x2 v = {lo, hi}; bf16x2_t b = __builtin_convertvector(v, bf16x2_t); return __builtin_bit_cast(unsigned, b); }
; __device__ __forceinline__ float bf2f(unsigned u16) { return __uint_as_float(u16 << 16); }
; __device__ __forceinline__ float silu(float g) { return g / (1.f + __expf(-g)); }
; template <int MODE>
; __device__ __forceinline__ void attn_unit(const UnitP& P, ALAS char* lds, const float* __restrict__ sub_gain, const int wv0, unsigned& hgen, unsigned* qctr, const int xcd) {
;     ...
; #pragma unroll
;             for (int d0 = 0; d0 < 4; ++d0)
; #pragma unroll
;                 for (int g = 0; g < 4; ++g) {
;                     const u32x2 gg = *(const u32x2*)(gp + 32 * d0 + 8 * g);
;                     const float y0 = o[d0][4 * g + 0] * inv * silu(bf2f(gg.x & 0xffffu)), y1 = o[d0][4 * g + 1] * inv * silu(bf2f(gg.x >> 16));
;                     const float y2 = o[d0][4 * g + 2] * inv * silu(bf2f(gg.y & 0xffffu)), y3 = o[d0][4 * g + 3] * inv * silu(bf2f(gg.y >> 16));
;                     u32x2 w; w.x = cvtpk(y0, y1); w.y = cvtpk(y2, y3);
;                     *(u32x2*)(mp + 32 * d0 + 8 * g) = w;
	v_fmac_f32_e32 v84, v88, v84
	v_mul_f32_e32 v87, v78, v83
	v_fma_f32 v90, -v75, v86, v76
	v_fmac_f32_e32 v85, v89, v81
	v_mul_f32_e32 v88, v80, v84
	v_fma_f32 v91, -v77, v87, v78
	v_fmac_f32_e32 v86, v90, v82
	v_fma_f32 v73, -v73, v85, v74
	v_fma_f32 v92, -v79, v88, v80
	v_fmac_f32_e32 v87, v91, v83
	v_fma_f32 v74, -v75, v86, v76
	v_div_fmas_f32 v73, v73, v81, v85
	s_mov_b64 vcc, s[4:5]
	v_fmac_f32_e32 v88, v92, v84
	v_fma_f32 v75, -v77, v87, v78
	v_div_fixup_f32 v49, v73, v49, v70
	v_div_fmas_f32 v70, v74, v82, v86
	s_mov_b64 vcc, s[6:7]
	v_pk_mul_f32 v[54:55], v[54:55], v[66:67] op_sel_hi:[1,0]
	v_fma_f32 v76, -v79, v88, v80
	v_div_fixup_f32 v48, v70, v48, v67
	v_div_fmas_f32 v67, v75, v83, v87
	s_mov_b64 vcc, s[8:9]
	v_pk_mul_f32 v[48:49], v[52:53], v[48:49]
	v_div_fmas_f32 v52, v76, v84, v88
	v_div_fixup_f32 v51, v67, v51, v72
	v_div_fixup_f32 v50, v52, v50, v71
	v_pk_mul_f32 v[50:51], v[54:55], v[50:51]
	v_cvt_pk_bf16_f32 v48, v48, v49
	v_cvt_pk_bf16_f32 v49, v50, v51
	global_store_dwordx2 v[64:65], v[48:49], off offset:16
	v_mov_b32_e32 v48, v100
	v_mov_b32_e32 v49, v101
	v_lshlrev_b32_e32 v67, 16, v48
	v_and_b32_e32 v70, 0xffff0000, v48
	v_lshlrev_b32_e32 v71, 16, v49
	v_and_b32_e32 v72, 0xffff0000, v49
	v_mul_f32_e32 v48, 0xbfb8aa3b, v67
	v_mul_f32_e32 v49, 0xbfb8aa3b, v70
	v_exp_f32_e32 v48, v48
	v_exp_f32_e32 v49, v49
	v_mul_f32_e32 v50, 0xbfb8aa3b, v71
	v_mul_f32_e32 v51, 0xbfb8aa3b, v72
	v_exp_f32_e32 v50, v50
	v_exp_f32_e32 v51, v51
	v_pk_add_f32 v[48:49], v[48:49], 1.0 op_sel_hi:[1,0]
	v_pk_mul_f32 v[52:53], v[56:57], v[66:67] op_sel_hi:[1,0]
	v_div_scale_f32 v56, s[4:5], v49, v49, v70
	v_pk_mul_f32 v[54:55], v[58:59], v[66:67] op_sel_hi:[1,0]
	v_pk_add_f32 v[50:51], v[50:51], 1.0 op_sel_hi:[1,0]
	v_div_scale_f32 v58, s[4:5], v48, v48, v67
	v_rcp_f32_e32 v77, v56
	v_div_scale_f32 v73, s[6:7], v51, v51, v72
	v_rcp_f32_e32 v78, v58
	v_div_scale_f32 v75, s[8:9], v50, v50, v71
	v_rcp_f32_e32 v79, v73
	v_rcp_f32_e32 v80, v75
	v_fma_f32 v81, -v56, v77, 1.0
	v_div_scale_f32 v57, vcc, v70, v49, v70
	v_fma_f32 v82, -v58, v78, 1.0
	v_fmac_f32_e32 v77, v81, v77
	v_div_scale_f32 v59, s[4:5], v67, v48, v67
	v_fma_f32 v83, -v73, v79, 1.0
	v_fmac_f32_e32 v78, v82, v78
	v_mul_f32_e32 v81, v57, v77
	v_div_scale_f32 v74, s[6:7], v72, v51, v72
	v_fma_f32 v84, -v75, v80, 1.0
	v_fmac_f32_e32 v79, v83, v79
	v_mul_f32_e32 v82, v59, v78
	v_fma_f32 v85, -v56, v81, v57
	v_div_scale_f32 v76, s[8:9], v71, v50, v71
	v_fmac_f32_e32 v80, v84, v80
	v_mul_f32_e32 v83, v74, v79
	v_fma_f32 v86, -v58, v82, v59
	v_fmac_f32_e32 v81, v85, v77
	v_mul_f32_e32 v84, v76, v80
	v_fma_f32 v87, -v73, v83, v74
	v_fmac_f32_e32 v82, v86, v78
	v_fma_f32 v56, -v56, v81, v57
	v_fma_f32 v88, -v75, v84, v76
	v_fmac_f32_e32 v83, v87, v79
	v_fma_f32 v57, -v58, v82, v59
	v_div_fmas_f32 v56, v56, v77, v81
	s_mov_b64 vcc, s[4:5]
	v_fmac_f32_e32 v84, v88, v80
	v_fma_f32 v58, -v73, v83, v74
	v_div_fixup_f32 v49, v56, v49, v70
	v_div_fmas_f32 v56, v57, v78, v82
	s_mov_b64 vcc, s[6:7]
	v_fma_f32 v59, -v75, v84, v76
	v_div_fixup_f32 v48, v56, v48, v67
	v_div_fmas_f32 v56, v58, v79, v83
	s_mov_b64 vcc, s[8:9]
	v_pk_mul_f32 v[48:49], v[52:53], v[48:49]
	v_div_fmas_f32 v52, v59, v80, v84
	v_div_fixup_f32 v51, v56, v51, v72
	v_div_fixup_f32 v50, v52, v50, v71
	v_pk_mul_f32 v[50:51], v[54:55], v[50:51]
	v_cvt_pk_bf16_f32 v48, v48, v49
	v_cvt_pk_bf16_f32 v49, v50, v51
	global_store_dwordx2 v[64:65], v[48:49], off offset:32
	v_mov_b32_e32 v48, v102
	v_mov_b32_e32 v49, v103
	v_pk_mul_f32 v[52:53], v[60:61], v[66:67] op_sel_hi:[1,0]
	v_pk_mul_f32 v[54:55], v[62:63], v[66:67] op_sel_hi:[1,0]
	v_lshlrev_b32_e32 v56, 16, v48
	v_and_b32_e32 v57, 0xffff0000, v48
	v_lshlrev_b32_e32 v58, 16, v49
	v_and_b32_e32 v59, 0xffff0000, v49
	v_mul_f32_e32 v48, 0xbfb8aa3b, v56
	v_mul_f32_e32 v49, 0xbfb8aa3b, v57
	v_exp_f32_e32 v48, v48
	v_exp_f32_e32 v49, v49
	v_mul_f32_e32 v50, 0xbfb8aa3b, v58
	v_mul_f32_e32 v51, 0xbfb8aa3b, v59
	v_exp_f32_e32 v50, v50
	v_exp_f32_e32 v51, v51
	v_pk_add_f32 v[48:49], v[48:49], 1.0 op_sel_hi:[1,0]
	v_pk_add_f32 v[50:51], v[50:51], 1.0 op_sel_hi:[1,0]
	v_div_scale_f32 v60, s[4:5], v49, v49, v57
	v_div_scale_f32 v62, s[4:5], v48, v48, v56
	v_rcp_f32_e32 v73, v60
	v_div_scale_f32 v67, s[6:7], v51, v51, v59
	v_rcp_f32_e32 v74, v62
	v_div_scale_f32 v71, s[8:9], v50, v50, v58
	v_rcp_f32_e32 v75, v67
	v_rcp_f32_e32 v76, v71
	v_fma_f32 v77, -v60, v73, 1.0
	v_div_scale_f32 v61, vcc, v57, v49, v57
	v_fma_f32 v78, -v62, v74, 1.0
	v_fmac_f32_e32 v73, v77, v73
	v_div_scale_f32 v63, s[4:5], v56, v48, v56
	v_fma_f32 v79, -v67, v75, 1.0
	v_fmac_f32_e32 v74, v78, v74
	v_mul_f32_e32 v77, v61, v73
	v_div_scale_f32 v70, s[6:7], v59, v51, v59
	v_fma_f32 v80, -v71, v76, 1.0
	v_fmac_f32_e32 v75, v79, v75
	v_mul_f32_e32 v78, v63, v74
	v_fma_f32 v81, -v60, v77, v61
	v_div_scale_f32 v72, s[8:9], v58, v50, v58
	v_fmac_f32_e32 v76, v80, v76
	v_mul_f32_e32 v79, v70, v75
	v_fma_f32 v82, -v62, v78, v63
	v_fmac_f32_e32 v77, v81, v73
	v_mul_f32_e32 v80, v72, v76
	v_fma_f32 v83, -v67, v79, v70
	v_fmac_f32_e32 v78, v82, v74
	v_fma_f32 v60, -v60, v77, v61
	v_fma_f32 v84, -v71, v80, v72
	v_fmac_f32_e32 v79, v83, v75
	v_fma_f32 v61, -v62, v78, v63
	v_div_fmas_f32 v60, v60, v73, v77
	s_mov_b64 vcc, s[4:5]
	v_fmac_f32_e32 v80, v84, v76
	v_fma_f32 v62, -v67, v79, v70
	v_div_fixup_f32 v49, v60, v49, v57
	v_div_fmas_f32 v57, v61, v74, v78
	s_mov_b64 vcc, s[6:7]
	v_fma_f32 v63, -v71, v80, v72
	v_div_fixup_f32 v48, v57, v48, v56
	v_div_fmas_f32 v56, v62, v75, v79
	s_mov_b64 vcc, s[8:9]
	v_pk_mul_f32 v[48:49], v[52:53], v[48:49]
	v_div_fmas_f32 v52, v63, v76, v80
	v_div_fixup_f32 v51, v56, v51, v59
	v_div_fixup_f32 v50, v52, v50, v58
; __device__ __forceinline__ unsigned cvtpk(float lo, float hi) { f32x2 v = {lo, hi}; bf16x2_t b = __builtin_convertvector(v, bf16x2_t); return __builtin_bit_cast(unsigned, b); }
; __device__ __forceinline__ float bf2f(unsigned u16) { return __uint_as_float(u16 << 16); }
; __device__ __forceinline__ float silu(float g) { return g / (1.f + __expf(-g)); }
; template <int MODE>
; __device__ __forceinline__ void attn_unit(const UnitP& P, ALAS char* lds, const float* __restrict__ sub_gain, const int wv0, unsigned& hgen, unsigned* qctr, const int xcd) {
;     ...
; #pragma unroll
;             for (int d0 = 0; d0 < 4; ++d0)
; #pragma unroll
;                 for (int g = 0; g < 4; ++g) {
;                     const u32x2 gg = *(const u32x2*)(gp + 32 * d0 + 8 * g);
;                     const float y0 = o[d0][4 * g + 0] * inv * silu(bf2f(gg.x & 0xffffu)), y1 = o[d0][4 * g + 1] * inv * silu(bf2f(gg.x >> 16));
;                     const float y2 = o[d0][4 * g + 2] * inv * silu(bf2f(gg.y & 0xffffu)), y3 = o[d0][4 * g + 3] * inv * silu(bf2f(gg.y >> 16));
;                     u32x2 w; w.x = cvtpk(y0, y1); w.y = cvtpk(y2, y3);
;                     *(u32x2*)(mp + 32 * d0 + 8 * g) = w;
	v_pk_mul_f32 v[50:51], v[54:55], v[50:51]
	v_cvt_pk_bf16_f32 v48, v48, v49
	v_cvt_pk_bf16_f32 v49, v50, v51
	global_store_dwordx2 v[64:65], v[48:49], off offset:48
	v_mov_b32_e32 v48, v104
	v_mov_b32_e32 v49, v105
	v_pk_mul_f32 v[32:33], v[32:33], v[66:67] op_sel_hi:[1,0]
	v_pk_mul_f32 v[34:35], v[34:35], v[66:67] op_sel_hi:[1,0]
	v_lshlrev_b32_e32 v52, 16, v48
	v_and_b32_e32 v53, 0xffff0000, v48
	v_lshlrev_b32_e32 v54, 16, v49
	v_and_b32_e32 v55, 0xffff0000, v49
	v_mul_f32_e32 v48, 0xbfb8aa3b, v52
	v_mul_f32_e32 v49, 0xbfb8aa3b, v53
	v_exp_f32_e32 v48, v48
	v_exp_f32_e32 v49, v49
	v_mul_f32_e32 v50, 0xbfb8aa3b, v54
	v_mul_f32_e32 v51, 0xbfb8aa3b, v55
	v_exp_f32_e32 v50, v50
	v_exp_f32_e32 v51, v51
	v_pk_add_f32 v[48:49], v[48:49], 1.0 op_sel_hi:[1,0]
	v_pk_add_f32 v[50:51], v[50:51], 1.0 op_sel_hi:[1,0]
	v_div_scale_f32 v56, s[4:5], v49, v49, v53
	v_div_scale_f32 v58, s[4:5], v48, v48, v52
	v_rcp_f32_e32 v67, v56
	v_div_scale_f32 v60, s[6:7], v51, v51, v55
	v_rcp_f32_e32 v70, v58
	v_div_scale_f32 v62, s[8:9], v50, v50, v54
	v_rcp_f32_e32 v71, v60
	v_rcp_f32_e32 v72, v62
	v_fma_f32 v73, -v56, v67, 1.0
	v_div_scale_f32 v57, vcc, v53, v49, v53
	v_fma_f32 v74, -v58, v70, 1.0
	v_fmac_f32_e32 v67, v73, v67
	v_div_scale_f32 v59, s[4:5], v52, v48, v52
	v_fma_f32 v75, -v60, v71, 1.0
	v_fmac_f32_e32 v70, v74, v70
	v_mul_f32_e32 v73, v57, v67
	v_div_scale_f32 v61, s[6:7], v55, v51, v55
	v_fma_f32 v76, -v62, v72, 1.0
	v_fmac_f32_e32 v71, v75, v71
	v_mul_f32_e32 v74, v59, v70
	v_fma_f32 v77, -v56, v73, v57
	v_div_scale_f32 v63, s[8:9], v54, v50, v54
	v_fmac_f32_e32 v72, v76, v72
	v_mul_f32_e32 v75, v61, v71
	v_fma_f32 v78, -v58, v74, v59
	v_fmac_f32_e32 v73, v77, v67
	v_mul_f32_e32 v76, v63, v72
	v_fma_f32 v79, -v60, v75, v61
	v_fmac_f32_e32 v74, v78, v70
	v_fma_f32 v56, -v56, v73, v57
	v_fma_f32 v80, -v62, v76, v63
	v_fmac_f32_e32 v75, v79, v71
	v_fma_f32 v57, -v58, v74, v59
	v_div_fmas_f32 v56, v56, v67, v73
	s_mov_b64 vcc, s[4:5]
	v_fmac_f32_e32 v76, v80, v72
	v_fma_f32 v58, -v60, v75, v61
	v_div_fixup_f32 v49, v56, v49, v53
	v_div_fmas_f32 v53, v57, v70, v74
	s_mov_b64 vcc, s[6:7]
	v_fma_f32 v59, -v62, v76, v63
	v_div_fixup_f32 v48, v53, v48, v52
	v_div_fmas_f32 v52, v58, v71, v75
	s_mov_b64 vcc, s[8:9]
	v_pk_mul_f32 v[32:33], v[32:33], v[48:49]
	v_div_fmas_f32 v48, v59, v72, v76
	v_div_fixup_f32 v49, v52, v51, v55
	v_div_fixup_f32 v48, v48, v50, v54
	v_pk_mul_f32 v[34:35], v[34:35], v[48:49]
	v_cvt_pk_bf16_f32 v32, v32, v33
	v_cvt_pk_bf16_f32 v33, v34, v35
	global_store_dwordx2 v[64:65], v[32:33], off offset:64
	v_mov_b32_e32 v32, v106
	v_mov_b32_e32 v33, v107
	v_pk_mul_f32 v[36:37], v[36:37], v[66:67] op_sel_hi:[1,0]
	v_pk_mul_f32 v[38:39], v[38:39], v[66:67] op_sel_hi:[1,0]
	v_lshlrev_b32_e32 v48, 16, v32
	v_and_b32_e32 v49, 0xffff0000, v32
	v_lshlrev_b32_e32 v50, 16, v33
	v_and_b32_e32 v51, 0xffff0000, v33
	v_mul_f32_e32 v32, 0xbfb8aa3b, v48
	v_mul_f32_e32 v33, 0xbfb8aa3b, v49
	v_exp_f32_e32 v32, v32
	v_exp_f32_e32 v33, v33
	v_mul_f32_e32 v34, 0xbfb8aa3b, v50
	v_mul_f32_e32 v35, 0xbfb8aa3b, v51
	v_exp_f32_e32 v34, v34
	v_exp_f32_e32 v35, v35
	v_pk_add_f32 v[32:33], v[32:33], 1.0 op_sel_hi:[1,0]
	v_pk_add_f32 v[34:35], v[34:35], 1.0 op_sel_hi:[1,0]
	v_div_scale_f32 v52, s[4:5], v33, v33, v49
	v_div_scale_f32 v54, s[4:5], v32, v32, v48
	v_rcp_f32_e32 v60, v52
	v_div_scale_f32 v56, s[6:7], v35, v35, v51
	v_rcp_f32_e32 v61, v54
	v_div_scale_f32 v58, s[8:9], v34, v34, v50
	v_rcp_f32_e32 v62, v56
	v_rcp_f32_e32 v63, v58
	v_fma_f32 v67, -v52, v60, 1.0
	v_div_scale_f32 v53, vcc, v49, v33, v49
	v_fma_f32 v70, -v54, v61, 1.0
	v_fmac_f32_e32 v60, v67, v60
	v_div_scale_f32 v55, s[4:5], v48, v32, v48
	v_fma_f32 v71, -v56, v62, 1.0
	v_fmac_f32_e32 v61, v70, v61
	v_mul_f32_e32 v67, v53, v60
	v_div_scale_f32 v57, s[6:7], v51, v35, v51
	v_fma_f32 v72, -v58, v63, 1.0
	v_fmac_f32_e32 v62, v71, v62
	v_mul_f32_e32 v70, v55, v61
	v_fma_f32 v73, -v52, v67, v53
	v_div_scale_f32 v59, s[8:9], v50, v34, v50
	v_fmac_f32_e32 v63, v72, v63
	v_mul_f32_e32 v71, v57, v62
	v_fma_f32 v74, -v54, v70, v55
	v_fmac_f32_e32 v67, v73, v60
	v_mul_f32_e32 v72, v59, v63
	v_fma_f32 v75, -v56, v71, v57
	v_fmac_f32_e32 v70, v74, v61
	v_fma_f32 v52, -v52, v67, v53
	v_fma_f32 v76, -v58, v72, v59
	v_fmac_f32_e32 v71, v75, v62
	v_fma_f32 v53, -v54, v70, v55
	v_div_fmas_f32 v52, v52, v60, v67
	s_mov_b64 vcc, s[4:5]
	v_fmac_f32_e32 v72, v76, v63
	v_fma_f32 v54, -v56, v71, v57
	v_div_fixup_f32 v33, v52, v33, v49
	v_div_fmas_f32 v49, v53, v61, v70
	s_mov_b64 vcc, s[6:7]
	v_fma_f32 v55, -v58, v72, v59
	v_div_fixup_f32 v32, v49, v32, v48
	v_div_fmas_f32 v48, v54, v62, v71
	s_mov_b64 vcc, s[8:9]
	v_pk_mul_f32 v[32:33], v[36:37], v[32:33]
	v_div_fmas_f32 v36, v55, v63, v72
	v_div_fixup_f32 v35, v48, v35, v51
	v_div_fixup_f32 v34, v36, v34, v50
	v_pk_mul_f32 v[34:35], v[38:39], v[34:35]
	v_cvt_pk_bf16_f32 v32, v32, v33
	v_cvt_pk_bf16_f32 v33, v34, v35
	global_store_dwordx2 v[64:65], v[32:33], off offset:80
	v_mov_b32_e32 v32, v108
	v_mov_b32_e32 v33, v109
	v_pk_mul_f32 v[36:37], v[40:41], v[66:67] op_sel_hi:[1,0]
	v_pk_mul_f32 v[38:39], v[42:43], v[66:67] op_sel_hi:[1,0]
	v_lshlrev_b32_e32 v48, 16, v32
	v_and_b32_e32 v49, 0xffff0000, v32
	v_lshlrev_b32_e32 v50, 16, v33
	v_and_b32_e32 v51, 0xffff0000, v33
	v_mul_f32_e32 v32, 0xbfb8aa3b, v48
	v_mul_f32_e32 v33, 0xbfb8aa3b, v49
	v_exp_f32_e32 v32, v32
	v_exp_f32_e32 v33, v33
	v_mul_f32_e32 v34, 0xbfb8aa3b, v50
	v_mul_f32_e32 v35, 0xbfb8aa3b, v51
	v_exp_f32_e32 v34, v34
	v_exp_f32_e32 v35, v35
	v_pk_add_f32 v[32:33], v[32:33], 1.0 op_sel_hi:[1,0]
	v_pk_add_f32 v[34:35], v[34:35], 1.0 op_sel_hi:[1,0]
	v_div_scale_f32 v40, s[4:5], v33, v33, v49
; __device__ __forceinline__ unsigned cvtpk(float lo, float hi) { f32x2 v = {lo, hi}; bf16x2_t b = __builtin_convertvector(v, bf16x2_t); return __builtin_bit_cast(unsigned, b); }
; __device__ __forceinline__ float bf2f(unsigned u16) { return __uint_as_float(u16 << 16); }
; __device__ __forceinline__ float silu(float g) { return g / (1.f + __expf(-g)); }
; template <int MODE>
; __device__ __forceinline__ void attn_unit(const UnitP& P, ALAS char* lds, const float* __restrict__ sub_gain, const int wv0, unsigned& hgen, unsigned* qctr, const int xcd) {
;     ...
; #pragma unroll
;             for (int d0 = 0; d0 < 4; ++d0)
; #pragma unroll
;                 for (int g = 0; g < 4; ++g) {
;                     const u32x2 gg = *(const u32x2*)(gp + 32 * d0 + 8 * g);
;                     const float y0 = o[d0][4 * g + 0] * inv * silu(bf2f(gg.x & 0xffffu)), y1 = o[d0][4 * g + 1] * inv * silu(bf2f(gg.x >> 16));
;                     const float y2 = o[d0][4 * g + 2] * inv * silu(bf2f(gg.y & 0xffffu)), y3 = o[d0][4 * g + 3] * inv * silu(bf2f(gg.y >> 16));
;                     u32x2 w; w.x = cvtpk(y0, y1); w.y = cvtpk(y2, y3);
;                     *(u32x2*)(mp + 32 * d0 + 8 * g) = w;
	v_div_scale_f32 v42, s[4:5], v32, v32, v48
	v_rcp_f32_e32 v56, v40
	v_div_scale_f32 v52, s[6:7], v35, v35, v51
	v_rcp_f32_e32 v57, v42
	v_div_scale_f32 v54, s[8:9], v34, v34, v50
	v_rcp_f32_e32 v58, v52
	v_rcp_f32_e32 v59, v54
	v_fma_f32 v60, -v40, v56, 1.0
	v_div_scale_f32 v41, vcc, v49, v33, v49
	v_fma_f32 v61, -v42, v57, 1.0
	v_fmac_f32_e32 v56, v60, v56
	v_div_scale_f32 v43, s[4:5], v48, v32, v48
	v_fma_f32 v62, -v52, v58, 1.0
	v_fmac_f32_e32 v57, v61, v57
	v_mul_f32_e32 v60, v41, v56
	v_div_scale_f32 v53, s[6:7], v51, v35, v51
	v_fma_f32 v63, -v54, v59, 1.0
	v_fmac_f32_e32 v58, v62, v58
	v_mul_f32_e32 v61, v43, v57
	v_fma_f32 v67, -v40, v60, v41
	v_div_scale_f32 v55, s[8:9], v50, v34, v50
	v_fmac_f32_e32 v59, v63, v59
	v_mul_f32_e32 v62, v53, v58
	v_fma_f32 v70, -v42, v61, v43
	v_fmac_f32_e32 v60, v67, v56
	v_mul_f32_e32 v63, v55, v59
	v_fma_f32 v71, -v52, v62, v53
	v_fmac_f32_e32 v61, v70, v57
	v_fma_f32 v40, -v40, v60, v41
	v_fma_f32 v72, -v54, v63, v55
	v_fmac_f32_e32 v62, v71, v58
	v_fma_f32 v41, -v42, v61, v43
	v_div_fmas_f32 v40, v40, v56, v60
	s_mov_b64 vcc, s[4:5]
	v_fmac_f32_e32 v63, v72, v59
	v_fma_f32 v42, -v52, v62, v53
	v_div_fixup_f32 v33, v40, v33, v49
	v_div_fmas_f32 v40, v41, v57, v61
	s_mov_b64 vcc, s[6:7]
	v_fma_f32 v43, -v54, v63, v55
	v_div_fixup_f32 v32, v40, v32, v48
	v_div_fmas_f32 v40, v42, v58, v62
	s_mov_b64 vcc, s[8:9]
	v_pk_mul_f32 v[32:33], v[36:37], v[32:33]
	v_div_fmas_f32 v36, v43, v59, v63
	v_div_fixup_f32 v35, v40, v35, v51
	v_div_fixup_f32 v34, v36, v34, v50
	v_pk_mul_f32 v[34:35], v[38:39], v[34:35]
	v_cvt_pk_bf16_f32 v32, v32, v33
	v_cvt_pk_bf16_f32 v33, v34, v35
	global_store_dwordx2 v[64:65], v[32:33], off offset:96
	v_mov_b32_e32 v32, v110
	v_mov_b32_e32 v33, v111
	v_pk_mul_f32 v[36:37], v[44:45], v[66:67] op_sel_hi:[1,0]
	v_pk_mul_f32 v[38:39], v[46:47], v[66:67] op_sel_hi:[1,0]
	v_pk_mul_f32 v[16:17], v[16:17], v[66:67] op_sel_hi:[1,0]
	v_pk_mul_f32 v[18:19], v[18:19], v[66:67] op_sel_hi:[1,0]
	v_pk_mul_f32 v[20:21], v[20:21], v[66:67] op_sel_hi:[1,0]
	v_pk_mul_f32 v[22:23], v[22:23], v[66:67] op_sel_hi:[1,0]
	v_pk_mul_f32 v[0:1], v[0:1], v[66:67] op_sel_hi:[1,0]
	v_pk_mul_f32 v[2:3], v[2:3], v[66:67] op_sel_hi:[1,0]
	v_pk_mul_f32 v[4:5], v[4:5], v[66:67] op_sel_hi:[1,0]
	v_pk_mul_f32 v[6:7], v[6:7], v[66:67] op_sel_hi:[1,0]
	v_lshlrev_b32_e32 v40, 16, v32
	v_and_b32_e32 v41, 0xffff0000, v32
	v_lshlrev_b32_e32 v42, 16, v33
	v_and_b32_e32 v43, 0xffff0000, v33
	v_mul_f32_e32 v32, 0xbfb8aa3b, v40
	v_mul_f32_e32 v33, 0xbfb8aa3b, v41
	v_exp_f32_e32 v32, v32
	v_exp_f32_e32 v33, v33
	v_mul_f32_e32 v34, 0xbfb8aa3b, v42
	v_mul_f32_e32 v35, 0xbfb8aa3b, v43
	v_exp_f32_e32 v34, v34
	v_exp_f32_e32 v35, v35
	v_pk_add_f32 v[32:33], v[32:33], 1.0 op_sel_hi:[1,0]
	v_pk_add_f32 v[34:35], v[34:35], 1.0 op_sel_hi:[1,0]
	v_div_scale_f32 v44, s[4:5], v33, v33, v41
	v_div_scale_f32 v46, s[4:5], v32, v32, v40
	v_rcp_f32_e32 v52, v44
	v_div_scale_f32 v48, s[6:7], v35, v35, v43
	v_rcp_f32_e32 v53, v46
	v_div_scale_f32 v50, s[8:9], v34, v34, v42
	v_rcp_f32_e32 v54, v48
	v_rcp_f32_e32 v55, v50
	v_fma_f32 v56, -v44, v52, 1.0
	v_div_scale_f32 v45, vcc, v41, v33, v41
	v_fma_f32 v57, -v46, v53, 1.0
	v_fmac_f32_e32 v52, v56, v52
	v_div_scale_f32 v47, s[4:5], v40, v32, v40
	v_fma_f32 v58, -v48, v54, 1.0
	v_fmac_f32_e32 v53, v57, v53
	v_mul_f32_e32 v56, v45, v52
	v_div_scale_f32 v49, s[6:7], v43, v35, v43
	v_fma_f32 v59, -v50, v55, 1.0
	v_fmac_f32_e32 v54, v58, v54
	v_mul_f32_e32 v57, v47, v53
	v_fma_f32 v60, -v44, v56, v45
	v_div_scale_f32 v51, s[8:9], v42, v34, v42
	v_fmac_f32_e32 v55, v59, v55
	v_mul_f32_e32 v58, v49, v54
	v_fma_f32 v61, -v46, v57, v47
	v_fmac_f32_e32 v56, v60, v52
	v_mul_f32_e32 v59, v51, v55
	v_fma_f32 v62, -v48, v58, v49
	v_fmac_f32_e32 v57, v61, v53
	v_fma_f32 v44, -v44, v56, v45
	v_fma_f32 v63, -v50, v59, v51
	v_fmac_f32_e32 v58, v62, v54
	v_fma_f32 v45, -v46, v57, v47
	v_div_fmas_f32 v44, v44, v52, v56
	s_mov_b64 vcc, s[4:5]
	v_fmac_f32_e32 v59, v63, v55
	v_fma_f32 v46, -v48, v58, v49
	v_div_fixup_f32 v33, v44, v33, v41
	v_div_fmas_f32 v41, v45, v53, v57
	s_mov_b64 vcc, s[6:7]
	v_fma_f32 v47, -v50, v59, v51
	v_div_fixup_f32 v32, v41, v32, v40
	v_div_fmas_f32 v40, v46, v54, v58
	s_mov_b64 vcc, s[8:9]
	v_pk_mul_f32 v[32:33], v[36:37], v[32:33]
	v_div_fmas_f32 v36, v47, v55, v59
	v_div_fixup_f32 v35, v40, v35, v43
	v_div_fixup_f32 v34, v36, v34, v42
	v_pk_mul_f32 v[34:35], v[38:39], v[34:35]
	v_cvt_pk_bf16_f32 v32, v32, v33
	v_cvt_pk_bf16_f32 v33, v34, v35
	global_store_dwordx2 v[64:65], v[32:33], off offset:112
	v_mov_b32_e32 v32, v112
	v_mov_b32_e32 v33, v113
	v_lshlrev_b32_e32 v36, 16, v32
	v_and_b32_e32 v37, 0xffff0000, v32
	v_lshlrev_b32_e32 v38, 16, v33
	v_and_b32_e32 v39, 0xffff0000, v33
	v_mul_f32_e32 v32, 0xbfb8aa3b, v36
	v_mul_f32_e32 v33, 0xbfb8aa3b, v37
	v_exp_f32_e32 v32, v32
	v_exp_f32_e32 v33, v33
	v_mul_f32_e32 v34, 0xbfb8aa3b, v38
	v_mul_f32_e32 v35, 0xbfb8aa3b, v39
	v_exp_f32_e32 v34, v34
	v_exp_f32_e32 v35, v35
	v_pk_add_f32 v[32:33], v[32:33], 1.0 op_sel_hi:[1,0]
	v_pk_add_f32 v[34:35], v[34:35], 1.0 op_sel_hi:[1,0]
	v_div_scale_f32 v40, s[4:5], v33, v33, v37
	v_div_scale_f32 v42, s[4:5], v32, v32, v36
	v_rcp_f32_e32 v48, v40
	v_div_scale_f32 v44, s[6:7], v35, v35, v39
	v_rcp_f32_e32 v49, v42
	v_div_scale_f32 v46, s[8:9], v34, v34, v38
	v_rcp_f32_e32 v50, v44
	v_rcp_f32_e32 v51, v46
	v_fma_f32 v52, -v40, v48, 1.0
	v_div_scale_f32 v41, vcc, v37, v33, v37
	v_fma_f32 v53, -v42, v49, 1.0
	v_fmac_f32_e32 v48, v52, v48
	v_div_scale_f32 v43, s[4:5], v36, v32, v36
	v_fma_f32 v54, -v44, v50, 1.0
	v_fmac_f32_e32 v49, v53, v49
	v_mul_f32_e32 v52, v41, v48
	v_div_scale_f32 v45, s[6:7], v39, v35, v39
; __device__ __forceinline__ unsigned cvtpk(float lo, float hi) { f32x2 v = {lo, hi}; bf16x2_t b = __builtin_convertvector(v, bf16x2_t); return __builtin_bit_cast(unsigned, b); }
; __device__ __forceinline__ float bf2f(unsigned u16) { return __uint_as_float(u16 << 16); }
; __device__ __forceinline__ float silu(float g) { return g / (1.f + __expf(-g)); }
; template <int MODE>
; __device__ __forceinline__ void attn_unit(const UnitP& P, ALAS char* lds, const float* __restrict__ sub_gain, const int wv0, unsigned& hgen, unsigned* qctr, const int xcd) {
;     ...
; #pragma unroll
;             for (int d0 = 0; d0 < 4; ++d0)
; #pragma unroll
;                 for (int g = 0; g < 4; ++g) {
;                     const u32x2 gg = *(const u32x2*)(gp + 32 * d0 + 8 * g);
;                     const float y0 = o[d0][4 * g + 0] * inv * silu(bf2f(gg.x & 0xffffu)), y1 = o[d0][4 * g + 1] * inv * silu(bf2f(gg.x >> 16));
;                     const float y2 = o[d0][4 * g + 2] * inv * silu(bf2f(gg.y & 0xffffu)), y3 = o[d0][4 * g + 3] * inv * silu(bf2f(gg.y >> 16));
;                     u32x2 w; w.x = cvtpk(y0, y1); w.y = cvtpk(y2, y3);
;                     *(u32x2*)(mp + 32 * d0 + 8 * g) = w;
	v_fma_f32 v55, -v46, v51, 1.0
	v_fmac_f32_e32 v50, v54, v50
	v_mul_f32_e32 v53, v43, v49
	v_fma_f32 v56, -v40, v52, v41
	v_div_scale_f32 v47, s[8:9], v38, v34, v38
	v_fmac_f32_e32 v51, v55, v51
	v_mul_f32_e32 v54, v45, v50
	v_fma_f32 v57, -v42, v53, v43
	v_fmac_f32_e32 v52, v56, v48
	v_mul_f32_e32 v55, v47, v51
	v_fma_f32 v58, -v44, v54, v45
	v_fmac_f32_e32 v53, v57, v49
	v_fma_f32 v40, -v40, v52, v41
	v_fma_f32 v59, -v46, v55, v47
	v_fmac_f32_e32 v54, v58, v50
	v_fma_f32 v41, -v42, v53, v43
	v_div_fmas_f32 v40, v40, v48, v52
	s_mov_b64 vcc, s[4:5]
	v_fmac_f32_e32 v55, v59, v51
	v_fma_f32 v42, -v44, v54, v45
	v_div_fixup_f32 v33, v40, v33, v37
	v_div_fmas_f32 v37, v41, v49, v53
	s_mov_b64 vcc, s[6:7]
	v_fma_f32 v43, -v46, v55, v47
	v_div_fixup_f32 v32, v37, v32, v36
	v_div_fmas_f32 v36, v42, v50, v54
	s_mov_b64 vcc, s[8:9]
	v_pk_mul_f32 v[16:17], v[16:17], v[32:33]
	v_div_fmas_f32 v32, v43, v51, v55
	v_div_fixup_f32 v33, v36, v35, v39
	v_div_fixup_f32 v32, v32, v34, v38
	v_pk_mul_f32 v[18:19], v[18:19], v[32:33]
	v_cvt_pk_bf16_f32 v16, v16, v17
	v_cvt_pk_bf16_f32 v17, v18, v19
	global_store_dwordx2 v[64:65], v[16:17], off offset:128
	v_mov_b32_e32 v16, v114
	v_mov_b32_e32 v17, v115
	v_lshlrev_b32_e32 v32, 16, v16
	v_and_b32_e32 v33, 0xffff0000, v16
	v_lshlrev_b32_e32 v34, 16, v17
	v_and_b32_e32 v35, 0xffff0000, v17
	v_mul_f32_e32 v16, 0xbfb8aa3b, v32
	v_mul_f32_e32 v17, 0xbfb8aa3b, v33
	v_exp_f32_e32 v16, v16
	v_exp_f32_e32 v17, v17
	v_mul_f32_e32 v18, 0xbfb8aa3b, v34
	v_mul_f32_e32 v19, 0xbfb8aa3b, v35
	v_exp_f32_e32 v18, v18
	v_exp_f32_e32 v19, v19
	v_pk_add_f32 v[16:17], v[16:17], 1.0 op_sel_hi:[1,0]
	v_pk_add_f32 v[18:19], v[18:19], 1.0 op_sel_hi:[1,0]
	v_div_scale_f32 v36, s[4:5], v17, v17, v33
	v_div_scale_f32 v38, s[4:5], v16, v16, v32
	v_rcp_f32_e32 v44, v36
	v_div_scale_f32 v40, s[6:7], v19, v19, v35
	v_rcp_f32_e32 v45, v38
	v_div_scale_f32 v42, s[8:9], v18, v18, v34
	v_rcp_f32_e32 v46, v40
	v_rcp_f32_e32 v47, v42
	v_fma_f32 v48, -v36, v44, 1.0
	v_div_scale_f32 v37, vcc, v33, v17, v33
	v_fma_f32 v49, -v38, v45, 1.0
	v_fmac_f32_e32 v44, v48, v44
	v_div_scale_f32 v39, s[4:5], v32, v16, v32
	v_fma_f32 v50, -v40, v46, 1.0
	v_fmac_f32_e32 v45, v49, v45
	v_mul_f32_e32 v48, v37, v44
	v_div_scale_f32 v41, s[6:7], v35, v19, v35
	v_fma_f32 v51, -v42, v47, 1.0
	v_fmac_f32_e32 v46, v50, v46
	v_mul_f32_e32 v49, v39, v45
	v_fma_f32 v52, -v36, v48, v37
	v_div_scale_f32 v43, s[8:9], v34, v18, v34
	v_fmac_f32_e32 v47, v51, v47
	v_mul_f32_e32 v50, v41, v46
	v_fma_f32 v53, -v38, v49, v39
	v_fmac_f32_e32 v48, v52, v44
	v_mul_f32_e32 v51, v43, v47
	v_fma_f32 v54, -v40, v50, v41
	v_fmac_f32_e32 v49, v53, v45
	v_fma_f32 v36, -v36, v48, v37
	v_fma_f32 v55, -v42, v51, v43
	v_fmac_f32_e32 v50, v54, v46
	v_fma_f32 v37, -v38, v49, v39
	v_div_fmas_f32 v36, v36, v44, v48
	s_mov_b64 vcc, s[4:5]
	v_fmac_f32_e32 v51, v55, v47
	v_fma_f32 v38, -v40, v50, v41
	v_div_fixup_f32 v17, v36, v17, v33
	v_div_fmas_f32 v33, v37, v45, v49
	s_mov_b64 vcc, s[6:7]
	v_fma_f32 v39, -v42, v51, v43
	v_div_fixup_f32 v16, v33, v16, v32
	v_div_fmas_f32 v32, v38, v46, v50
	s_mov_b64 vcc, s[8:9]
	v_pk_mul_f32 v[16:17], v[20:21], v[16:17]
	v_div_fmas_f32 v20, v39, v47, v51
	v_div_fixup_f32 v19, v32, v19, v35
	v_div_fixup_f32 v18, v20, v18, v34
	v_pk_mul_f32 v[18:19], v[22:23], v[18:19]
	v_cvt_pk_bf16_f32 v16, v16, v17
	v_cvt_pk_bf16_f32 v17, v18, v19
	global_store_dwordx2 v[64:65], v[16:17], off offset:144
	v_mov_b32_e32 v16, v116
	v_mov_b32_e32 v17, v117
	v_pk_mul_f32 v[20:21], v[24:25], v[66:67] op_sel_hi:[1,0]
	v_pk_mul_f32 v[22:23], v[26:27], v[66:67] op_sel_hi:[1,0]
	v_lshlrev_b32_e32 v32, 16, v16
	v_and_b32_e32 v33, 0xffff0000, v16
	v_lshlrev_b32_e32 v34, 16, v17
	v_and_b32_e32 v35, 0xffff0000, v17
	v_mul_f32_e32 v16, 0xbfb8aa3b, v32
	v_mul_f32_e32 v17, 0xbfb8aa3b, v33
	v_exp_f32_e32 v16, v16
	v_exp_f32_e32 v17, v17
	v_mul_f32_e32 v18, 0xbfb8aa3b, v34
	v_mul_f32_e32 v19, 0xbfb8aa3b, v35
	v_exp_f32_e32 v18, v18
	v_exp_f32_e32 v19, v19
	v_pk_add_f32 v[16:17], v[16:17], 1.0 op_sel_hi:[1,0]
	v_pk_add_f32 v[18:19], v[18:19], 1.0 op_sel_hi:[1,0]
	v_div_scale_f32 v24, s[4:5], v17, v17, v33
	v_div_scale_f32 v26, s[4:5], v16, v16, v32
	v_rcp_f32_e32 v40, v24
	v_div_scale_f32 v36, s[6:7], v19, v19, v35
	v_rcp_f32_e32 v41, v26
	v_div_scale_f32 v38, s[8:9], v18, v18, v34
	v_rcp_f32_e32 v42, v36
	v_rcp_f32_e32 v43, v38
	v_fma_f32 v44, -v24, v40, 1.0
	v_div_scale_f32 v25, vcc, v33, v17, v33
	v_fma_f32 v45, -v26, v41, 1.0
	v_fmac_f32_e32 v40, v44, v40
	v_div_scale_f32 v27, s[4:5], v32, v16, v32
	v_fma_f32 v46, -v36, v42, 1.0
	v_fmac_f32_e32 v41, v45, v41
	v_mul_f32_e32 v44, v25, v40
	v_div_scale_f32 v37, s[6:7], v35, v19, v35
	v_fma_f32 v47, -v38, v43, 1.0
	v_fmac_f32_e32 v42, v46, v42
	v_mul_f32_e32 v45, v27, v41
	v_fma_f32 v48, -v24, v44, v25
	v_div_scale_f32 v39, s[8:9], v34, v18, v34
	v_fmac_f32_e32 v43, v47, v43
	v_mul_f32_e32 v46, v37, v42
	v_fma_f32 v49, -v26, v45, v27
	v_fmac_f32_e32 v44, v48, v40
	v_mul_f32_e32 v47, v39, v43
	v_fma_f32 v50, -v36, v46, v37
	v_fmac_f32_e32 v45, v49, v41
	v_fma_f32 v24, -v24, v44, v25
	v_fma_f32 v51, -v38, v47, v39
	v_fmac_f32_e32 v46, v50, v42
	v_fma_f32 v25, -v26, v45, v27
	v_div_fmas_f32 v24, v24, v40, v44
	s_mov_b64 vcc, s[4:5]
	v_fmac_f32_e32 v47, v51, v43
	v_fma_f32 v26, -v36, v46, v37
	v_div_fixup_f32 v17, v24, v17, v33
	v_div_fmas_f32 v24, v25, v41, v45
	s_mov_b64 vcc, s[6:7]
	v_fma_f32 v27, -v38, v47, v39
	v_div_fixup_f32 v16, v24, v16, v32
	v_div_fmas_f32 v24, v26, v42, v46
	s_mov_b64 vcc, s[8:9]
	v_pk_mul_f32 v[16:17], v[20:21], v[16:17]
	v_div_fmas_f32 v20, v27, v43, v47
	v_div_fixup_f32 v19, v24, v19, v35
	v_div_fixup_f32 v18, v20, v18, v34
; __device__ __forceinline__ unsigned cvtpk(float lo, float hi) { f32x2 v = {lo, hi}; bf16x2_t b = __builtin_convertvector(v, bf16x2_t); return __builtin_bit_cast(unsigned, b); }
; __device__ __forceinline__ float bf2f(unsigned u16) { return __uint_as_float(u16 << 16); }
; __device__ __forceinline__ float silu(float g) { return g / (1.f + __expf(-g)); }
; template <int MODE>
; __device__ __forceinline__ void attn_unit(const UnitP& P, ALAS char* lds, const float* __restrict__ sub_gain, const int wv0, unsigned& hgen, unsigned* qctr, const int xcd) {
;     ...
; #pragma unroll
;             for (int d0 = 0; d0 < 4; ++d0)
; #pragma unroll
;                 for (int g = 0; g < 4; ++g) {
;                     const u32x2 gg = *(const u32x2*)(gp + 32 * d0 + 8 * g);
;                     const float y0 = o[d0][4 * g + 0] * inv * silu(bf2f(gg.x & 0xffffu)), y1 = o[d0][4 * g + 1] * inv * silu(bf2f(gg.x >> 16));
;                     const float y2 = o[d0][4 * g + 2] * inv * silu(bf2f(gg.y & 0xffffu)), y3 = o[d0][4 * g + 3] * inv * silu(bf2f(gg.y >> 16));
;                     u32x2 w; w.x = cvtpk(y0, y1); w.y = cvtpk(y2, y3);
;                     *(u32x2*)(mp + 32 * d0 + 8 * g) = w;
	v_pk_mul_f32 v[18:19], v[22:23], v[18:19]
	v_cvt_pk_bf16_f32 v16, v16, v17
	v_cvt_pk_bf16_f32 v17, v18, v19
	global_store_dwordx2 v[64:65], v[16:17], off offset:160
	v_mov_b32_e32 v16, v118
	v_mov_b32_e32 v17, v119
	v_pk_mul_f32 v[20:21], v[28:29], v[66:67] op_sel_hi:[1,0]
	v_pk_mul_f32 v[22:23], v[30:31], v[66:67] op_sel_hi:[1,0]
	v_lshlrev_b32_e32 v24, 16, v16
	v_and_b32_e32 v25, 0xffff0000, v16
	v_lshlrev_b32_e32 v26, 16, v17
	v_and_b32_e32 v27, 0xffff0000, v17
	v_mul_f32_e32 v16, 0xbfb8aa3b, v24
	v_mul_f32_e32 v17, 0xbfb8aa3b, v25
	v_exp_f32_e32 v16, v16
	v_exp_f32_e32 v17, v17
	v_mul_f32_e32 v18, 0xbfb8aa3b, v26
	v_mul_f32_e32 v19, 0xbfb8aa3b, v27
	v_exp_f32_e32 v18, v18
	v_exp_f32_e32 v19, v19
	v_pk_add_f32 v[16:17], v[16:17], 1.0 op_sel_hi:[1,0]
	v_pk_add_f32 v[18:19], v[18:19], 1.0 op_sel_hi:[1,0]
	v_div_scale_f32 v28, s[4:5], v17, v17, v25
	v_div_scale_f32 v30, s[4:5], v16, v16, v24
	v_rcp_f32_e32 v36, v28
	v_div_scale_f32 v32, s[6:7], v19, v19, v27
	v_rcp_f32_e32 v37, v30
	v_div_scale_f32 v34, s[8:9], v18, v18, v26
	v_rcp_f32_e32 v38, v32
	v_rcp_f32_e32 v39, v34
	v_fma_f32 v40, -v28, v36, 1.0
	v_div_scale_f32 v29, vcc, v25, v17, v25
	v_fma_f32 v41, -v30, v37, 1.0
	v_fmac_f32_e32 v36, v40, v36
	v_div_scale_f32 v31, s[4:5], v24, v16, v24
	v_fma_f32 v42, -v32, v38, 1.0
	v_fmac_f32_e32 v37, v41, v37
	v_mul_f32_e32 v40, v29, v36
	v_div_scale_f32 v33, s[6:7], v27, v19, v27
	v_fma_f32 v43, -v34, v39, 1.0
	v_fmac_f32_e32 v38, v42, v38
	v_mul_f32_e32 v41, v31, v37
	v_fma_f32 v44, -v28, v40, v29
	v_div_scale_f32 v35, s[8:9], v26, v18, v26
	v_fmac_f32_e32 v39, v43, v39
	v_mul_f32_e32 v42, v33, v38
	v_fma_f32 v45, -v30, v41, v31
	v_fmac_f32_e32 v40, v44, v36
	v_mul_f32_e32 v43, v35, v39
	v_fma_f32 v46, -v32, v42, v33
	v_fmac_f32_e32 v41, v45, v37
	v_fma_f32 v28, -v28, v40, v29
	v_fma_f32 v47, -v34, v43, v35
	v_fmac_f32_e32 v42, v46, v38
	v_fma_f32 v29, -v30, v41, v31
	v_div_fmas_f32 v28, v28, v36, v40
	s_mov_b64 vcc, s[4:5]
	v_fmac_f32_e32 v43, v47, v39
	v_fma_f32 v30, -v32, v42, v33
	v_div_fixup_f32 v17, v28, v17, v25
	v_div_fmas_f32 v25, v29, v37, v41
	s_mov_b64 vcc, s[6:7]
	v_fma_f32 v31, -v34, v43, v35
	v_div_fixup_f32 v16, v25, v16, v24
	v_div_fmas_f32 v24, v30, v38, v42
	s_mov_b64 vcc, s[8:9]
	v_pk_mul_f32 v[16:17], v[20:21], v[16:17]
	v_div_fmas_f32 v20, v31, v39, v43
	v_div_fixup_f32 v19, v24, v19, v27
	v_div_fixup_f32 v18, v20, v18, v26
	v_pk_mul_f32 v[18:19], v[22:23], v[18:19]
	v_cvt_pk_bf16_f32 v16, v16, v17
	v_cvt_pk_bf16_f32 v17, v18, v19
	global_store_dwordx2 v[64:65], v[16:17], off offset:176
	v_mov_b32_e32 v16, v120
	v_mov_b32_e32 v17, v121
	v_lshlrev_b32_e32 v20, 16, v16
	v_and_b32_e32 v21, 0xffff0000, v16
	v_lshlrev_b32_e32 v22, 16, v17
	v_and_b32_e32 v23, 0xffff0000, v17
	v_mul_f32_e32 v16, 0xbfb8aa3b, v20
	v_mul_f32_e32 v17, 0xbfb8aa3b, v21
	v_exp_f32_e32 v16, v16
	v_exp_f32_e32 v17, v17
	v_mul_f32_e32 v18, 0xbfb8aa3b, v22
	v_mul_f32_e32 v19, 0xbfb8aa3b, v23
	v_exp_f32_e32 v18, v18
	v_exp_f32_e32 v19, v19
	v_pk_add_f32 v[16:17], v[16:17], 1.0 op_sel_hi:[1,0]
	v_pk_add_f32 v[18:19], v[18:19], 1.0 op_sel_hi:[1,0]
	v_div_scale_f32 v24, s[4:5], v17, v17, v21
	v_div_scale_f32 v26, s[4:5], v16, v16, v20
	v_rcp_f32_e32 v32, v24
	v_div_scale_f32 v28, s[6:7], v19, v19, v23
	v_rcp_f32_e32 v33, v26
	v_div_scale_f32 v30, s[8:9], v18, v18, v22
	v_rcp_f32_e32 v34, v28
	v_rcp_f32_e32 v35, v30
	v_fma_f32 v36, -v24, v32, 1.0
	v_div_scale_f32 v25, vcc, v21, v17, v21
	v_fma_f32 v37, -v26, v33, 1.0
	v_fmac_f32_e32 v32, v36, v32
	v_div_scale_f32 v27, s[4:5], v20, v16, v20
	v_fma_f32 v38, -v28, v34, 1.0
	v_fmac_f32_e32 v33, v37, v33
	v_mul_f32_e32 v36, v25, v32
	v_div_scale_f32 v29, s[6:7], v23, v19, v23
	v_fma_f32 v39, -v30, v35, 1.0
	v_fmac_f32_e32 v34, v38, v34
	v_mul_f32_e32 v37, v27, v33
	v_fma_f32 v40, -v24, v36, v25
	v_div_scale_f32 v31, s[8:9], v22, v18, v22
	v_fmac_f32_e32 v35, v39, v35
	v_mul_f32_e32 v38, v29, v34
	v_fma_f32 v41, -v26, v37, v27
	v_fmac_f32_e32 v36, v40, v32
	v_mul_f32_e32 v39, v31, v35
	v_fma_f32 v42, -v28, v38, v29
	v_fmac_f32_e32 v37, v41, v33
	v_fma_f32 v24, -v24, v36, v25
	v_fma_f32 v43, -v30, v39, v31
	v_fmac_f32_e32 v38, v42, v34
	v_fma_f32 v25, -v26, v37, v27
	v_div_fmas_f32 v24, v24, v32, v36
	s_mov_b64 vcc, s[4:5]
	v_fmac_f32_e32 v39, v43, v35
	v_fma_f32 v26, -v28, v38, v29
	v_div_fixup_f32 v17, v24, v17, v21
	v_div_fmas_f32 v21, v25, v33, v37
	s_mov_b64 vcc, s[6:7]
	v_fma_f32 v27, -v30, v39, v31
	v_div_fixup_f32 v16, v21, v16, v20
	v_div_fmas_f32 v20, v26, v34, v38
	s_mov_b64 vcc, s[8:9]
	v_pk_mul_f32 v[0:1], v[0:1], v[16:17]
	v_div_fmas_f32 v16, v27, v35, v39
	v_div_fixup_f32 v17, v20, v19, v23
	v_div_fixup_f32 v16, v16, v18, v22
	v_pk_mul_f32 v[2:3], v[2:3], v[16:17]
	v_cvt_pk_bf16_f32 v0, v0, v1
	v_cvt_pk_bf16_f32 v1, v2, v3
	global_store_dwordx2 v[64:65], v[0:1], off offset:192
	v_mov_b32_e32 v0, v122
	v_mov_b32_e32 v1, v123
	v_lshlrev_b32_e32 v16, 16, v0
	v_and_b32_e32 v17, 0xffff0000, v0
	v_lshlrev_b32_e32 v18, 16, v1
	v_and_b32_e32 v19, 0xffff0000, v1
	v_mul_f32_e32 v0, 0xbfb8aa3b, v16
	v_mul_f32_e32 v1, 0xbfb8aa3b, v17
	v_exp_f32_e32 v0, v0
	v_exp_f32_e32 v1, v1
	v_mul_f32_e32 v2, 0xbfb8aa3b, v18
	v_mul_f32_e32 v3, 0xbfb8aa3b, v19
	v_exp_f32_e32 v2, v2
	v_exp_f32_e32 v3, v3
	v_pk_add_f32 v[0:1], v[0:1], 1.0 op_sel_hi:[1,0]
	v_pk_add_f32 v[2:3], v[2:3], 1.0 op_sel_hi:[1,0]
	v_div_scale_f32 v20, s[4:5], v1, v1, v17
	v_div_scale_f32 v22, s[4:5], v0, v0, v16
	v_rcp_f32_e32 v28, v20
	v_div_scale_f32 v24, s[6:7], v3, v3, v19
	v_rcp_f32_e32 v29, v22
	v_div_scale_f32 v26, s[8:9], v2, v2, v18
	v_rcp_f32_e32 v30, v24
	v_rcp_f32_e32 v31, v26
	v_fma_f32 v32, -v20, v28, 1.0
	v_div_scale_f32 v21, vcc, v17, v1, v17
; __device__ __forceinline__ unsigned cvtpk(float lo, float hi) { f32x2 v = {lo, hi}; bf16x2_t b = __builtin_convertvector(v, bf16x2_t); return __builtin_bit_cast(unsigned, b); }
; __device__ __forceinline__ float bf2f(unsigned u16) { return __uint_as_float(u16 << 16); }
; __device__ __forceinline__ float silu(float g) { return g / (1.f + __expf(-g)); }
; template <int MODE>
; __device__ __forceinline__ void attn_unit(const UnitP& P, ALAS char* lds, const float* __restrict__ sub_gain, const int wv0, unsigned& hgen, unsigned* qctr, const int xcd) {
;     ...
; #pragma unroll
;             for (int d0 = 0; d0 < 4; ++d0)
; #pragma unroll
;                 for (int g = 0; g < 4; ++g) {
;                     const u32x2 gg = *(const u32x2*)(gp + 32 * d0 + 8 * g);
;                     const float y0 = o[d0][4 * g + 0] * inv * silu(bf2f(gg.x & 0xffffu)), y1 = o[d0][4 * g + 1] * inv * silu(bf2f(gg.x >> 16));
;                     const float y2 = o[d0][4 * g + 2] * inv * silu(bf2f(gg.y & 0xffffu)), y3 = o[d0][4 * g + 3] * inv * silu(bf2f(gg.y >> 16));
;                     u32x2 w; w.x = cvtpk(y0, y1); w.y = cvtpk(y2, y3);
;                     *(u32x2*)(mp + 32 * d0 + 8 * g) = w;
	v_fma_f32 v33, -v22, v29, 1.0
	v_fmac_f32_e32 v28, v32, v28
	v_div_scale_f32 v23, s[4:5], v16, v0, v16
	v_fma_f32 v34, -v24, v30, 1.0
	v_fmac_f32_e32 v29, v33, v29
	v_mul_f32_e32 v32, v21, v28
	v_div_scale_f32 v25, s[6:7], v19, v3, v19
	v_fma_f32 v35, -v26, v31, 1.0
	v_fmac_f32_e32 v30, v34, v30
	v_mul_f32_e32 v33, v23, v29
	v_fma_f32 v36, -v20, v32, v21
	v_div_scale_f32 v27, s[8:9], v18, v2, v18
	v_fmac_f32_e32 v31, v35, v31
	v_mul_f32_e32 v34, v25, v30
	v_fma_f32 v37, -v22, v33, v23
	v_fmac_f32_e32 v32, v36, v28
	v_mul_f32_e32 v35, v27, v31
	v_fma_f32 v38, -v24, v34, v25
	v_fmac_f32_e32 v33, v37, v29
	v_fma_f32 v20, -v20, v32, v21
	v_fma_f32 v39, -v26, v35, v27
	v_fmac_f32_e32 v34, v38, v30
	v_fma_f32 v21, -v22, v33, v23
	v_div_fmas_f32 v20, v20, v28, v32
	s_mov_b64 vcc, s[4:5]
	v_fmac_f32_e32 v35, v39, v31
	v_fma_f32 v22, -v24, v34, v25
	v_div_fixup_f32 v1, v20, v1, v17
	v_div_fmas_f32 v17, v21, v29, v33
	s_mov_b64 vcc, s[6:7]
	v_fma_f32 v23, -v26, v35, v27
	v_div_fixup_f32 v0, v17, v0, v16
	v_div_fmas_f32 v16, v22, v30, v34
	s_mov_b64 vcc, s[8:9]
	v_pk_mul_f32 v[0:1], v[4:5], v[0:1]
	v_div_fmas_f32 v4, v23, v31, v35
	v_div_fixup_f32 v3, v16, v3, v19
	v_div_fixup_f32 v2, v4, v2, v18
	v_pk_mul_f32 v[2:3], v[6:7], v[2:3]
	v_cvt_pk_bf16_f32 v0, v0, v1
	v_cvt_pk_bf16_f32 v1, v2, v3
	global_store_dwordx2 v[64:65], v[0:1], off offset:208
	v_mov_b32_e32 v0, v124
	v_mov_b32_e32 v1, v125
	v_pk_mul_f32 v[4:5], v[8:9], v[66:67] op_sel_hi:[1,0]
	v_pk_mul_f32 v[6:7], v[10:11], v[66:67] op_sel_hi:[1,0]
	v_lshlrev_b32_e32 v16, 16, v0
	v_and_b32_e32 v17, 0xffff0000, v0
	v_lshlrev_b32_e32 v18, 16, v1
	v_and_b32_e32 v19, 0xffff0000, v1
	v_mul_f32_e32 v0, 0xbfb8aa3b, v16
	v_mul_f32_e32 v1, 0xbfb8aa3b, v17
	v_exp_f32_e32 v0, v0
	v_exp_f32_e32 v1, v1
	v_mul_f32_e32 v2, 0xbfb8aa3b, v18
	v_mul_f32_e32 v3, 0xbfb8aa3b, v19
	v_exp_f32_e32 v2, v2
	v_exp_f32_e32 v3, v3
	v_pk_add_f32 v[0:1], v[0:1], 1.0 op_sel_hi:[1,0]
	v_pk_add_f32 v[2:3], v[2:3], 1.0 op_sel_hi:[1,0]
	v_div_scale_f32 v8, s[4:5], v1, v1, v17
	v_div_scale_f32 v10, s[4:5], v0, v0, v16
	v_rcp_f32_e32 v24, v8
	v_div_scale_f32 v20, s[6:7], v3, v3, v19
	v_rcp_f32_e32 v25, v10
	v_div_scale_f32 v22, s[8:9], v2, v2, v18
	v_rcp_f32_e32 v26, v20
	v_rcp_f32_e32 v27, v22
	v_fma_f32 v28, -v8, v24, 1.0
	v_div_scale_f32 v9, vcc, v17, v1, v17
	v_fma_f32 v29, -v10, v25, 1.0
	v_fmac_f32_e32 v24, v28, v24
	v_div_scale_f32 v11, s[4:5], v16, v0, v16
	v_fma_f32 v30, -v20, v26, 1.0
	v_fmac_f32_e32 v25, v29, v25
	v_mul_f32_e32 v28, v9, v24
	v_div_scale_f32 v21, s[6:7], v19, v3, v19
	v_fma_f32 v31, -v22, v27, 1.0
	v_fmac_f32_e32 v26, v30, v26
	v_mul_f32_e32 v29, v11, v25
	v_fma_f32 v32, -v8, v28, v9
	v_div_scale_f32 v23, s[8:9], v18, v2, v18
	v_fmac_f32_e32 v27, v31, v27
	v_mul_f32_e32 v30, v21, v26
	v_fma_f32 v33, -v10, v29, v11
	v_fmac_f32_e32 v28, v32, v24
	v_mul_f32_e32 v31, v23, v27
	v_fma_f32 v34, -v20, v30, v21
	v_fmac_f32_e32 v29, v33, v25
	v_fma_f32 v8, -v8, v28, v9
	v_fma_f32 v35, -v22, v31, v23
	v_fmac_f32_e32 v30, v34, v26
	v_fma_f32 v9, -v10, v29, v11
	v_div_fmas_f32 v8, v8, v24, v28
	s_mov_b64 vcc, s[4:5]
	v_fmac_f32_e32 v31, v35, v27
	v_fma_f32 v10, -v20, v30, v21
	v_div_fixup_f32 v1, v8, v1, v17
	v_div_fmas_f32 v8, v9, v25, v29
	s_mov_b64 vcc, s[6:7]
	v_fma_f32 v11, -v22, v31, v23
	v_div_fixup_f32 v0, v8, v0, v16
	v_div_fmas_f32 v8, v10, v26, v30
	s_mov_b64 vcc, s[8:9]
	v_pk_mul_f32 v[0:1], v[4:5], v[0:1]
	v_div_fmas_f32 v4, v11, v27, v31
	v_div_fixup_f32 v3, v8, v3, v19
	v_div_fixup_f32 v2, v4, v2, v18
	v_pk_mul_f32 v[2:3], v[6:7], v[2:3]
	v_cvt_pk_bf16_f32 v0, v0, v1
	v_cvt_pk_bf16_f32 v1, v2, v3
	global_store_dwordx2 v[64:65], v[0:1], off offset:224
	v_mov_b32_e32 v0, v126
	v_mov_b32_e32 v1, v127
	v_pk_mul_f32 v[4:5], v[12:13], v[66:67] op_sel_hi:[1,0]
	v_pk_mul_f32 v[6:7], v[14:15], v[66:67] op_sel_hi:[1,0]
	v_lshlrev_b32_e32 v8, 16, v0
	v_and_b32_e32 v9, 0xffff0000, v0
	v_lshlrev_b32_e32 v10, 16, v1
	v_and_b32_e32 v11, 0xffff0000, v1
	v_mul_f32_e32 v0, 0xbfb8aa3b, v8
	v_mul_f32_e32 v1, 0xbfb8aa3b, v9
	v_exp_f32_e32 v0, v0
	v_exp_f32_e32 v1, v1
	v_mul_f32_e32 v2, 0xbfb8aa3b, v10
	v_mul_f32_e32 v3, 0xbfb8aa3b, v11
	v_exp_f32_e32 v2, v2
	v_exp_f32_e32 v3, v3
	v_pk_add_f32 v[0:1], v[0:1], 1.0 op_sel_hi:[1,0]
	v_pk_add_f32 v[2:3], v[2:3], 1.0 op_sel_hi:[1,0]
	v_div_scale_f32 v12, s[4:5], v1, v1, v9
	v_div_scale_f32 v14, s[4:5], v0, v0, v8
	v_rcp_f32_e32 v20, v12
	v_div_scale_f32 v16, s[6:7], v3, v3, v11
	v_rcp_f32_e32 v21, v14
	v_div_scale_f32 v18, s[8:9], v2, v2, v10
	v_rcp_f32_e32 v22, v16
	v_rcp_f32_e32 v23, v18
	v_fma_f32 v24, -v12, v20, 1.0
	v_div_scale_f32 v13, vcc, v9, v1, v9
	v_fma_f32 v25, -v14, v21, 1.0
	v_fmac_f32_e32 v20, v24, v20
	v_div_scale_f32 v15, s[4:5], v8, v0, v8
	v_fma_f32 v26, -v16, v22, 1.0
	v_fmac_f32_e32 v21, v25, v21
	v_mul_f32_e32 v24, v13, v20
	v_div_scale_f32 v17, s[6:7], v11, v3, v11
	v_fma_f32 v27, -v18, v23, 1.0
	v_fmac_f32_e32 v22, v26, v22
	v_mul_f32_e32 v25, v15, v21
	v_fma_f32 v28, -v12, v24, v13
	v_div_scale_f32 v19, s[8:9], v10, v2, v10
	v_fmac_f32_e32 v23, v27, v23
	v_mul_f32_e32 v26, v17, v22
	v_fma_f32 v29, -v14, v25, v15
	v_fmac_f32_e32 v24, v28, v20
	v_mul_f32_e32 v27, v19, v23
	v_fma_f32 v30, -v16, v26, v17
	v_fmac_f32_e32 v25, v29, v21
	v_fma_f32 v12, -v12, v24, v13
	v_fma_f32 v31, -v18, v27, v19
	v_fmac_f32_e32 v26, v30, v22
	v_fma_f32 v13, -v14, v25, v15
	v_div_fmas_f32 v12, v12, v20, v24
	s_mov_b64 vcc, s[4:5]
	v_fmac_f32_e32 v27, v31, v23
	v_fma_f32 v14, -v16, v26, v17
	v_div_fixup_f32 v1, v12, v1, v9
	v_div_fmas_f32 v9, v13, v21, v25
	s_mov_b64 vcc, s[6:7]
	v_fma_f32 v15, -v18, v27, v19
	v_div_fixup_f32 v0, v9, v0, v8
	v_div_fmas_f32 v8, v14, v22, v26
	s_mov_b64 vcc, s[8:9]
	v_pk_mul_f32 v[0:1], v[4:5], v[0:1]
	v_div_fmas_f32 v4, v15, v23, v27
	v_div_fixup_f32 v3, v8, v3, v11
	v_div_fixup_f32 v2, v4, v2, v10
	v_pk_mul_f32 v[2:3], v[6:7], v[2:3]
	v_cvt_pk_bf16_f32 v0, v0, v1
	v_cvt_pk_bf16_f32 v1, v2, v3
	global_store_dwordx2 v[64:65], v[0:1], off offset:240
	s_branch .LBB0_218
